# all per-segment s_setprio flips deleted from the six GEMM mainloops (A/B'd on repeated GU phases: -2 pct per phase)
# speedup vs baseline: 1.0036x; 1.0007x over previous
.LBB0_232:
	s_add_u32 s46, s48, 0xfffc0080
	s_addc_u32 s47, s49, -1
	s_add_i32 s69, 0, 0x10000
	s_cmp_eq_u32 s68, 12
	s_cselect_b32 s53, s19, s47
	s_cselect_b32 s52, s64, s46
	v_add_u32_e32 v170, s69, v159
	s_cselect_b32 s51, s17, s67
	s_cselect_b32 s50, s65, s66
	s_add_i32 s70, 0, 0x14000
	ds_read_b128 v[176:179], v170
	ds_read_b128 v[180:183], v170 offset:1024
	ds_read_b128 v[184:187], v170 offset:2048
	ds_read_b128 v[188:191], v170 offset:3072
	v_add_u32_e32 v170, s70, v159
	ds_read_b128 v[192:195], v170
	ds_read_b128 v[196:199], v170 offset:1024
	ds_read_b128 v[200:203], v170 offset:2048
	ds_read_b128 v[204:207], v170 offset:3072
	v_lshl_add_u64 v[170:171], s[48:49], 0, v[152:153]
	s_add_i32 m0, s55, 0xc000
	ds_read_b128 v[208:211], v161
	ds_read_b128 v[212:215], v161 offset:1024
	ds_read_b128 v[216:219], v161 offset:2048
	ds_read_b128 v[220:223], v161 offset:3072
	ds_read_b128 v[234:237], v161 offset:4096
	ds_read_b128 v[238:241], v161 offset:5120
	ds_read_b128 v[242:245], v161 offset:6144
	ds_read_b128 v[246:249], v161 offset:7168
	global_load_lds_dwordx4 v[170:171], off
	v_lshl_add_u64 v[170:171], s[48:49], 0, v[150:151]
	s_add_i32 m0, s55, 0xe000
	s_nop 0
	global_load_lds_dwordx4 v[170:171], off
	s_waitcnt vmcnt(8)
	s_waitcnt lgkmcnt(0)
	s_barrier
	s_waitcnt lgkmcnt(0)
	v_mfma_f32_16x16x32_bf16 v[140:143], v[176:179], v[208:211], v[140:143]
	v_mfma_f32_16x16x32_bf16 v[136:139], v[184:187], v[208:211], v[136:139]
	v_mfma_f32_16x16x32_bf16 v[128:131], v[176:179], v[216:219], v[128:131]
	v_mfma_f32_16x16x32_bf16 v[120:123], v[184:187], v[216:219], v[120:123]
	v_mfma_f32_16x16x32_bf16 v[112:115], v[176:179], v[234:237], v[112:115]
	v_mfma_f32_16x16x32_bf16 v[104:107], v[184:187], v[234:237], v[104:107]
	v_mfma_f32_16x16x32_bf16 v[96:99], v[176:179], v[242:245], v[96:99]
	v_mfma_f32_16x16x32_bf16 v[88:91], v[184:187], v[242:245], v[88:91]
	v_mfma_f32_16x16x32_bf16 v[140:143], v[180:183], v[212:215], v[140:143]
	v_mfma_f32_16x16x32_bf16 v[136:139], v[188:191], v[212:215], v[136:139]
	v_mfma_f32_16x16x32_bf16 v[128:131], v[180:183], v[220:223], v[128:131]
	v_mfma_f32_16x16x32_bf16 v[120:123], v[188:191], v[220:223], v[120:123]
	v_mfma_f32_16x16x32_bf16 v[112:115], v[180:183], v[238:241], v[112:115]
	v_mfma_f32_16x16x32_bf16 v[104:107], v[188:191], v[238:241], v[104:107]
	v_mfma_f32_16x16x32_bf16 v[96:99], v[180:183], v[246:249], v[96:99]
	v_mfma_f32_16x16x32_bf16 v[88:91], v[188:191], v[246:249], v[88:91]
	v_mfma_f32_16x16x32_bf16 v[132:135], v[192:195], v[208:211], v[132:135]
	v_mfma_f32_16x16x32_bf16 v[124:127], v[200:203], v[208:211], v[124:127]
	v_mfma_f32_16x16x32_bf16 v[116:119], v[192:195], v[216:219], v[116:119]
	v_mfma_f32_16x16x32_bf16 v[108:111], v[200:203], v[216:219], v[108:111]
	v_mfma_f32_16x16x32_bf16 v[100:103], v[192:195], v[234:237], v[100:103]
	v_mfma_f32_16x16x32_bf16 v[92:95], v[200:203], v[234:237], v[92:95]
	v_mfma_f32_16x16x32_bf16 v[84:87], v[192:195], v[242:245], v[84:87]
	v_mfma_f32_16x16x32_bf16 v[80:83], v[200:203], v[242:245], v[80:83]
	v_mfma_f32_16x16x32_bf16 v[132:135], v[196:199], v[212:215], v[132:135]
	v_mfma_f32_16x16x32_bf16 v[124:127], v[204:207], v[212:215], v[124:127]
	v_mfma_f32_16x16x32_bf16 v[116:119], v[196:199], v[220:223], v[116:119]
	v_mfma_f32_16x16x32_bf16 v[108:111], v[204:207], v[220:223], v[108:111]
	v_mfma_f32_16x16x32_bf16 v[100:103], v[196:199], v[238:241], v[100:103]
	v_mfma_f32_16x16x32_bf16 v[92:95], v[204:207], v[238:241], v[92:95]
	v_mfma_f32_16x16x32_bf16 v[84:87], v[196:199], v[246:249], v[84:87]
	v_mfma_f32_16x16x32_bf16 v[80:83], v[204:207], v[246:249], v[80:83]
	s_barrier
	s_add_i32 s46, s69, s54
	v_lshl_add_u64 v[170:171], s[50:51], 0, v[168:169]
	s_mov_b32 m0, s46
	ds_read_b128 v[208:211], v161 offset:16384
	ds_read_b128 v[212:215], v161 offset:17408
	ds_read_b128 v[216:219], v161 offset:18432
	ds_read_b128 v[220:223], v161 offset:19456
	ds_read_b128 v[234:237], v161 offset:20480
	ds_read_b128 v[238:241], v161 offset:21504
	ds_read_b128 v[242:245], v161 offset:22528
	ds_read_b128 v[246:249], v161 offset:23552
	global_load_lds_dwordx4 v[170:171], off
	s_add_i32 m0, s46, 0x2000
	s_add_u32 s46, s50, 0x40000
	v_lshl_add_u64 v[172:173], s[50:51], 0, v[148:149]
	s_addc_u32 s47, s51, 0
	s_add_i32 s69, s70, s54
	global_load_lds_dwordx4 v[172:173], off
	v_lshl_add_u64 v[224:225], s[46:47], 0, v[168:169]
	s_mov_b32 m0, s69
	v_lshl_add_u64 v[228:229], s[52:53], 0, v[146:147]
	global_load_lds_dwordx4 v[224:225], off
	v_lshl_add_u64 v[224:225], s[46:47], 0, v[148:149]
	s_add_i32 m0, s69, 0x2000
	s_nop 0
	global_load_lds_dwordx4 v[224:225], off
	v_lshl_add_u64 v[224:225], s[52:53], 0, v[144:145]
	s_mov_b32 m0, s55
	s_nop 0
	global_load_lds_dwordx4 v[224:225], off
	s_mov_b32 m0, s56
	s_nop 0
	global_load_lds_dwordx4 v[228:229], off
	s_waitcnt vmcnt(8)
	s_waitcnt lgkmcnt(0)
	s_barrier
	s_waitcnt lgkmcnt(0)
	v_mfma_f32_16x16x32_bf16 v[76:79], v[176:179], v[208:211], v[76:79]
	v_mfma_f32_16x16x32_bf16 v[72:75], v[184:187], v[208:211], v[72:75]
	v_mfma_f32_16x16x32_bf16 v[68:71], v[176:179], v[216:219], v[68:71]
	v_mfma_f32_16x16x32_bf16 v[60:63], v[184:187], v[216:219], v[60:63]
	v_mfma_f32_16x16x32_bf16 v[52:55], v[176:179], v[234:237], v[52:55]
	v_mfma_f32_16x16x32_bf16 v[44:47], v[184:187], v[234:237], v[44:47]
	v_mfma_f32_16x16x32_bf16 v[36:39], v[176:179], v[242:245], v[36:39]
	v_mfma_f32_16x16x32_bf16 v[28:31], v[184:187], v[242:245], v[28:31]
	v_mfma_f32_16x16x32_bf16 v[76:79], v[180:183], v[212:215], v[76:79]
	v_mfma_f32_16x16x32_bf16 v[72:75], v[188:191], v[212:215], v[72:75]
	v_mfma_f32_16x16x32_bf16 v[68:71], v[180:183], v[220:223], v[68:71]
	v_mfma_f32_16x16x32_bf16 v[60:63], v[188:191], v[220:223], v[60:63]
	v_mfma_f32_16x16x32_bf16 v[52:55], v[180:183], v[238:241], v[52:55]
	v_mfma_f32_16x16x32_bf16 v[44:47], v[188:191], v[238:241], v[44:47]
	v_mfma_f32_16x16x32_bf16 v[36:39], v[180:183], v[246:249], v[36:39]
	v_mfma_f32_16x16x32_bf16 v[28:31], v[188:191], v[246:249], v[28:31]
	v_mfma_f32_16x16x32_bf16 v[64:67], v[192:195], v[208:211], v[64:67]
	v_mfma_f32_16x16x32_bf16 v[56:59], v[200:203], v[208:211], v[56:59]
	v_mfma_f32_16x16x32_bf16 v[48:51], v[192:195], v[216:219], v[48:51]
	v_mfma_f32_16x16x32_bf16 v[40:43], v[200:203], v[216:219], v[40:43]
	v_mfma_f32_16x16x32_bf16 v[32:35], v[192:195], v[234:237], v[32:35]
	v_mfma_f32_16x16x32_bf16 v[24:27], v[200:203], v[234:237], v[24:27]
	v_mfma_f32_16x16x32_bf16 v[20:23], v[192:195], v[242:245], v[20:23]
	v_mfma_f32_16x16x32_bf16 v[16:19], v[200:203], v[242:245], v[16:19]
	v_mfma_f32_16x16x32_bf16 v[64:67], v[196:199], v[212:215], v[64:67]
	v_mfma_f32_16x16x32_bf16 v[56:59], v[204:207], v[212:215], v[56:59]
	v_mfma_f32_16x16x32_bf16 v[48:51], v[196:199], v[220:223], v[48:51]
	v_mfma_f32_16x16x32_bf16 v[40:43], v[204:207], v[220:223], v[40:43]
	v_mfma_f32_16x16x32_bf16 v[32:35], v[196:199], v[238:241], v[32:35]
	v_mfma_f32_16x16x32_bf16 v[24:27], v[204:207], v[238:241], v[24:27]
	v_mfma_f32_16x16x32_bf16 v[20:23], v[196:199], v[246:249], v[20:23]
	v_mfma_f32_16x16x32_bf16 v[16:19], v[204:207], v[246:249], v[16:19]
	s_barrier
	s_add_i32 s69, 0, 0x18000
	s_add_i32 s70, 0, 0x1c000
	v_add_u32_e32 v188, s69, v159
	v_add_u32_e32 v204, s70, v159
	ds_read_b128 v[176:179], v188
	ds_read_b128 v[180:183], v188 offset:1024
	ds_read_b128 v[184:187], v188 offset:2048
	ds_read_b128 v[188:191], v188 offset:3072
	ds_read_b128 v[192:195], v204
	ds_read_b128 v[196:199], v204 offset:1024
	ds_read_b128 v[200:203], v204 offset:2048
	ds_read_b128 v[204:207], v204 offset:3072
	s_add_u32 s46, s52, 0x40000
	s_addc_u32 s47, s53, 0
	s_mov_b32 m0, s57
	v_lshl_add_u64 v[250:251], s[46:47], 0, v[144:145]
	ds_read_b128 v[208:211], v161 offset:32768
	ds_read_b128 v[212:215], v161 offset:33792
	ds_read_b128 v[216:219], v161 offset:34816
	ds_read_b128 v[220:223], v161 offset:35840
	ds_read_b128 v[234:237], v161 offset:36864
	ds_read_b128 v[238:241], v161 offset:37888
	ds_read_b128 v[242:245], v161 offset:38912
	ds_read_b128 v[246:249], v161 offset:39936
	global_load_lds_dwordx4 v[250:251], off
	v_lshl_add_u64 v[250:251], s[46:47], 0, v[146:147]
	s_mov_b32 m0, s58
	s_nop 0
	global_load_lds_dwordx4 v[250:251], off
	s_waitcnt vmcnt(8)
	s_waitcnt lgkmcnt(0)
	s_barrier
	s_waitcnt lgkmcnt(0)
	v_mfma_f32_16x16x32_bf16 v[140:143], v[176:179], v[208:211], v[140:143]
	v_mfma_f32_16x16x32_bf16 v[136:139], v[184:187], v[208:211], v[136:139]
	v_mfma_f32_16x16x32_bf16 v[128:131], v[176:179], v[216:219], v[128:131]
	v_mfma_f32_16x16x32_bf16 v[120:123], v[184:187], v[216:219], v[120:123]
	v_mfma_f32_16x16x32_bf16 v[112:115], v[176:179], v[234:237], v[112:115]
	v_mfma_f32_16x16x32_bf16 v[104:107], v[184:187], v[234:237], v[104:107]
	v_mfma_f32_16x16x32_bf16 v[96:99], v[176:179], v[242:245], v[96:99]
	v_mfma_f32_16x16x32_bf16 v[88:91], v[184:187], v[242:245], v[88:91]
	v_mfma_f32_16x16x32_bf16 v[140:143], v[180:183], v[212:215], v[140:143]
	v_mfma_f32_16x16x32_bf16 v[136:139], v[188:191], v[212:215], v[136:139]
	v_mfma_f32_16x16x32_bf16 v[128:131], v[180:183], v[220:223], v[128:131]
	v_mfma_f32_16x16x32_bf16 v[120:123], v[188:191], v[220:223], v[120:123]
	v_mfma_f32_16x16x32_bf16 v[112:115], v[180:183], v[238:241], v[112:115]
	v_mfma_f32_16x16x32_bf16 v[104:107], v[188:191], v[238:241], v[104:107]
	v_mfma_f32_16x16x32_bf16 v[96:99], v[180:183], v[246:249], v[96:99]
	v_mfma_f32_16x16x32_bf16 v[88:91], v[188:191], v[246:249], v[88:91]
	v_mfma_f32_16x16x32_bf16 v[132:135], v[192:195], v[208:211], v[132:135]
	v_mfma_f32_16x16x32_bf16 v[124:127], v[200:203], v[208:211], v[124:127]
	v_mfma_f32_16x16x32_bf16 v[116:119], v[192:195], v[216:219], v[116:119]
	v_mfma_f32_16x16x32_bf16 v[108:111], v[200:203], v[216:219], v[108:111]
	v_mfma_f32_16x16x32_bf16 v[100:103], v[192:195], v[234:237], v[100:103]
	v_mfma_f32_16x16x32_bf16 v[92:95], v[200:203], v[234:237], v[92:95]
	v_mfma_f32_16x16x32_bf16 v[84:87], v[192:195], v[242:245], v[84:87]
	v_mfma_f32_16x16x32_bf16 v[80:83], v[200:203], v[242:245], v[80:83]
	v_mfma_f32_16x16x32_bf16 v[132:135], v[196:199], v[212:215], v[132:135]
	v_mfma_f32_16x16x32_bf16 v[124:127], v[204:207], v[212:215], v[124:127]
	v_mfma_f32_16x16x32_bf16 v[116:119], v[196:199], v[220:223], v[116:119]
	v_mfma_f32_16x16x32_bf16 v[108:111], v[204:207], v[220:223], v[108:111]
	v_mfma_f32_16x16x32_bf16 v[100:103], v[196:199], v[238:241], v[100:103]
	v_mfma_f32_16x16x32_bf16 v[92:95], v[204:207], v[238:241], v[92:95]
	v_mfma_f32_16x16x32_bf16 v[84:87], v[196:199], v[246:249], v[84:87]
	v_mfma_f32_16x16x32_bf16 v[80:83], v[204:207], v[246:249], v[80:83]
	s_barrier
	s_add_i32 s46, s69, s54
	v_lshl_add_u64 v[170:171], v[170:171], 0, s[36:37]
	s_mov_b32 m0, s46
	ds_read_b128 v[208:211], v161 offset:49152
	ds_read_b128 v[212:215], v161 offset:50176
	ds_read_b128 v[216:219], v161 offset:51200
	ds_read_b128 v[220:223], v161 offset:52224
	ds_read_b128 v[234:237], v161 offset:53248
	ds_read_b128 v[238:241], v161 offset:54272
	ds_read_b128 v[242:245], v161 offset:55296
	ds_read_b128 v[246:249], v161 offset:56320
	global_load_lds_dwordx4 v[170:171], off
	s_add_i32 m0, s46, 0x2000
	s_add_u32 s46, s50, 0x40080
	v_lshl_add_u64 v[170:171], v[172:173], 0, s[36:37]
	s_addc_u32 s47, s51, 0
	s_add_i32 s50, s70, s54
	global_load_lds_dwordx4 v[170:171], off
	v_lshl_add_u64 v[170:171], s[46:47], 0, v[168:169]
	s_mov_b32 m0, s50
	s_nop 0
	global_load_lds_dwordx4 v[170:171], off
	v_lshl_add_u64 v[170:171], s[46:47], 0, v[148:149]
	s_add_i32 m0, s50, 0x2000
	s_nop 0
	global_load_lds_dwordx4 v[170:171], off
	v_lshl_add_u64 v[170:171], v[224:225], 0, s[36:37]
	s_mov_b32 m0, s61
	s_nop 0
	global_load_lds_dwordx4 v[170:171], off
	v_lshl_add_u64 v[170:171], v[228:229], 0, s[36:37]
	s_mov_b32 m0, s62
	s_nop 0
	global_load_lds_dwordx4 v[170:171], off
	s_waitcnt vmcnt(8)
	s_waitcnt lgkmcnt(0)
	s_barrier
	s_waitcnt lgkmcnt(0)
	v_mfma_f32_16x16x32_bf16 v[76:79], v[176:179], v[208:211], v[76:79]
	v_mfma_f32_16x16x32_bf16 v[72:75], v[184:187], v[208:211], v[72:75]
	v_mfma_f32_16x16x32_bf16 v[68:71], v[176:179], v[216:219], v[68:71]
	v_mfma_f32_16x16x32_bf16 v[60:63], v[184:187], v[216:219], v[60:63]
	v_mfma_f32_16x16x32_bf16 v[52:55], v[176:179], v[234:237], v[52:55]
	v_mfma_f32_16x16x32_bf16 v[44:47], v[184:187], v[234:237], v[44:47]
	v_mfma_f32_16x16x32_bf16 v[36:39], v[176:179], v[242:245], v[36:39]
	v_mfma_f32_16x16x32_bf16 v[28:31], v[184:187], v[242:245], v[28:31]
	v_mfma_f32_16x16x32_bf16 v[76:79], v[180:183], v[212:215], v[76:79]
	v_mfma_f32_16x16x32_bf16 v[72:75], v[188:191], v[212:215], v[72:75]
	v_mfma_f32_16x16x32_bf16 v[68:71], v[180:183], v[220:223], v[68:71]
	v_mfma_f32_16x16x32_bf16 v[60:63], v[188:191], v[220:223], v[60:63]
	v_mfma_f32_16x16x32_bf16 v[52:55], v[180:183], v[238:241], v[52:55]
	v_mfma_f32_16x16x32_bf16 v[44:47], v[188:191], v[238:241], v[44:47]
	v_mfma_f32_16x16x32_bf16 v[36:39], v[180:183], v[246:249], v[36:39]
	v_mfma_f32_16x16x32_bf16 v[28:31], v[188:191], v[246:249], v[28:31]
	v_mfma_f32_16x16x32_bf16 v[64:67], v[192:195], v[208:211], v[64:67]
	v_mfma_f32_16x16x32_bf16 v[56:59], v[200:203], v[208:211], v[56:59]
	v_mfma_f32_16x16x32_bf16 v[48:51], v[192:195], v[216:219], v[48:51]
	v_mfma_f32_16x16x32_bf16 v[40:43], v[200:203], v[216:219], v[40:43]
	v_mfma_f32_16x16x32_bf16 v[32:35], v[192:195], v[234:237], v[32:35]
	v_mfma_f32_16x16x32_bf16 v[24:27], v[200:203], v[234:237], v[24:27]
	v_mfma_f32_16x16x32_bf16 v[20:23], v[192:195], v[242:245], v[20:23]
	v_mfma_f32_16x16x32_bf16 v[16:19], v[200:203], v[242:245], v[16:19]
	v_mfma_f32_16x16x32_bf16 v[64:67], v[196:199], v[212:215], v[64:67]
	v_mfma_f32_16x16x32_bf16 v[56:59], v[204:207], v[212:215], v[56:59]
	v_mfma_f32_16x16x32_bf16 v[48:51], v[196:199], v[220:223], v[48:51]
	v_mfma_f32_16x16x32_bf16 v[40:43], v[204:207], v[220:223], v[40:43]
	v_mfma_f32_16x16x32_bf16 v[32:35], v[196:199], v[238:241], v[32:35]
	v_mfma_f32_16x16x32_bf16 v[24:27], v[204:207], v[238:241], v[24:27]
	v_mfma_f32_16x16x32_bf16 v[20:23], v[196:199], v[246:249], v[20:23]
	v_mfma_f32_16x16x32_bf16 v[16:19], v[204:207], v[246:249], v[16:19]
	s_barrier
	s_add_i32 s68, s68, 2
	s_add_u32 s66, s66, 0x100
	s_addc_u32 s67, s67, 0
	s_add_u32 s48, s48, 0x100
	s_addc_u32 s49, s49, 0
	s_cmp_gt_u32 s68, 13
	s_cbranch_scc0 .LBB0_232
	s_and_b64 vcc, exec, s[14:15]
	s_cbranch_vccz .LBB0_235
	s_barrier

.LBB0_256:
	s_add_u32 s46, s48, 0xfffc0080
	s_addc_u32 s47, s49, -1
	s_add_i32 s67, 0, 0x10000
	s_cmp_eq_u32 s66, 12
	s_cselect_b32 s53, s19, s47
	s_cselect_b32 s52, s62, s46
	v_add_u32_e32 v163, s67, v157
	s_cselect_b32 s51, s17, s65
	s_cselect_b32 s50, s63, s64
	s_add_i32 s68, 0, 0x14000
	ds_read_b128 v[180:183], v163
	ds_read_b128 v[184:187], v163 offset:1024
	ds_read_b128 v[188:191], v163 offset:2048
	ds_read_b128 v[192:195], v163 offset:3072
	v_add_u32_e32 v163, s68, v157
	ds_read_b128 v[196:199], v163
	ds_read_b128 v[200:203], v163 offset:1024
	ds_read_b128 v[204:207], v163 offset:2048
	ds_read_b128 v[208:211], v163 offset:3072
	v_lshl_add_u64 v[170:171], s[48:49], 0, v[152:153]
	s_add_i32 m0, s54, 0xc000
	ds_read_b128 v[212:215], v161
	ds_read_b128 v[216:219], v161 offset:1024
	ds_read_b128 v[220:223], v161 offset:2048
	ds_read_b128 v[234:237], v161 offset:3072
	ds_read_b128 v[238:241], v161 offset:4096
	ds_read_b128 v[242:245], v161 offset:5120
	ds_read_b128 v[246:249], v161 offset:6144
	ds_read_b128 v[250:253], v161 offset:7168
	global_load_lds_dwordx4 v[170:171], off
	v_lshl_add_u64 v[170:171], s[48:49], 0, v[150:151]
	s_add_i32 m0, s54, 0xe000
	s_nop 0
	global_load_lds_dwordx4 v[170:171], off
	s_waitcnt vmcnt(8)
	s_waitcnt lgkmcnt(0)
	s_barrier
	s_waitcnt lgkmcnt(0)
	v_mfma_f32_16x16x32_bf16 v[140:143], v[180:183], v[212:215], v[140:143]
	v_mfma_f32_16x16x32_bf16 v[136:139], v[188:191], v[212:215], v[136:139]
	v_mfma_f32_16x16x32_bf16 v[128:131], v[180:183], v[220:223], v[128:131]
	v_mfma_f32_16x16x32_bf16 v[120:123], v[188:191], v[220:223], v[120:123]
	v_mfma_f32_16x16x32_bf16 v[112:115], v[180:183], v[238:241], v[112:115]
	v_mfma_f32_16x16x32_bf16 v[104:107], v[188:191], v[238:241], v[104:107]
	v_mfma_f32_16x16x32_bf16 v[96:99], v[180:183], v[246:249], v[96:99]
	v_mfma_f32_16x16x32_bf16 v[88:91], v[188:191], v[246:249], v[88:91]
	v_mfma_f32_16x16x32_bf16 v[140:143], v[184:187], v[216:219], v[140:143]
	v_mfma_f32_16x16x32_bf16 v[136:139], v[192:195], v[216:219], v[136:139]
	v_mfma_f32_16x16x32_bf16 v[128:131], v[184:187], v[234:237], v[128:131]
	v_mfma_f32_16x16x32_bf16 v[120:123], v[192:195], v[234:237], v[120:123]
	v_mfma_f32_16x16x32_bf16 v[112:115], v[184:187], v[242:245], v[112:115]
	v_mfma_f32_16x16x32_bf16 v[104:107], v[192:195], v[242:245], v[104:107]
	v_mfma_f32_16x16x32_bf16 v[96:99], v[184:187], v[250:253], v[96:99]
	v_mfma_f32_16x16x32_bf16 v[88:91], v[192:195], v[250:253], v[88:91]
	v_mfma_f32_16x16x32_bf16 v[132:135], v[196:199], v[212:215], v[132:135]
	v_mfma_f32_16x16x32_bf16 v[124:127], v[204:207], v[212:215], v[124:127]
	v_mfma_f32_16x16x32_bf16 v[116:119], v[196:199], v[220:223], v[116:119]
	v_mfma_f32_16x16x32_bf16 v[108:111], v[204:207], v[220:223], v[108:111]
	v_mfma_f32_16x16x32_bf16 v[100:103], v[196:199], v[238:241], v[100:103]
	v_mfma_f32_16x16x32_bf16 v[92:95], v[204:207], v[238:241], v[92:95]
	v_mfma_f32_16x16x32_bf16 v[84:87], v[196:199], v[246:249], v[84:87]
	v_mfma_f32_16x16x32_bf16 v[80:83], v[204:207], v[246:249], v[80:83]
	v_mfma_f32_16x16x32_bf16 v[132:135], v[200:203], v[216:219], v[132:135]
	v_mfma_f32_16x16x32_bf16 v[124:127], v[208:211], v[216:219], v[124:127]
	v_mfma_f32_16x16x32_bf16 v[116:119], v[200:203], v[234:237], v[116:119]
	v_mfma_f32_16x16x32_bf16 v[108:111], v[208:211], v[234:237], v[108:111]
	v_mfma_f32_16x16x32_bf16 v[100:103], v[200:203], v[242:245], v[100:103]
	v_mfma_f32_16x16x32_bf16 v[92:95], v[208:211], v[242:245], v[92:95]
	v_mfma_f32_16x16x32_bf16 v[84:87], v[200:203], v[250:253], v[84:87]
	v_mfma_f32_16x16x32_bf16 v[80:83], v[208:211], v[250:253], v[80:83]
	s_barrier
	s_add_i32 s46, s67, s43
	v_lshl_add_u64 v[170:171], s[50:51], 0, v[168:169]
	s_mov_b32 m0, s46
	ds_read_b128 v[212:215], v161 offset:16384
	ds_read_b128 v[216:219], v161 offset:17408
	ds_read_b128 v[220:223], v161 offset:18432
	ds_read_b128 v[234:237], v161 offset:19456
	ds_read_b128 v[238:241], v161 offset:20480
	ds_read_b128 v[242:245], v161 offset:21504
	ds_read_b128 v[246:249], v161 offset:22528
	ds_read_b128 v[250:253], v161 offset:23552
	global_load_lds_dwordx4 v[170:171], off
	s_add_i32 m0, s46, 0x2000
	s_add_u32 s46, s50, 0x40000
	v_lshl_add_u64 v[172:173], s[50:51], 0, v[148:149]
	s_addc_u32 s47, s51, 0
	s_add_i32 s67, s68, s43
	global_load_lds_dwordx4 v[172:173], off
	v_lshl_add_u64 v[224:225], s[46:47], 0, v[168:169]
	s_mov_b32 m0, s67
	v_lshl_add_u64 v[228:229], s[52:53], 0, v[146:147]
	global_load_lds_dwordx4 v[224:225], off
	v_lshl_add_u64 v[224:225], s[46:47], 0, v[148:149]
	s_add_i32 m0, s67, 0x2000
	s_nop 0
	global_load_lds_dwordx4 v[224:225], off
	v_lshl_add_u64 v[224:225], s[52:53], 0, v[144:145]
	s_mov_b32 m0, s54
	s_nop 0
	global_load_lds_dwordx4 v[224:225], off
	s_mov_b32 m0, s55
	s_nop 0
	global_load_lds_dwordx4 v[228:229], off
	s_waitcnt vmcnt(8)
	s_waitcnt lgkmcnt(0)
	s_barrier
	s_waitcnt lgkmcnt(0)
	v_mfma_f32_16x16x32_bf16 v[76:79], v[180:183], v[212:215], v[76:79]
	v_mfma_f32_16x16x32_bf16 v[72:75], v[188:191], v[212:215], v[72:75]
	v_mfma_f32_16x16x32_bf16 v[68:71], v[180:183], v[220:223], v[68:71]
	v_mfma_f32_16x16x32_bf16 v[60:63], v[188:191], v[220:223], v[60:63]
	v_mfma_f32_16x16x32_bf16 v[36:39], v[180:183], v[238:241], v[36:39]
	v_mfma_f32_16x16x32_bf16 v[28:31], v[188:191], v[238:241], v[28:31]
	v_mfma_f32_16x16x32_bf16 v[20:23], v[180:183], v[246:249], v[20:23]
	v_mfma_f32_16x16x32_bf16 v[12:15], v[188:191], v[246:249], v[12:15]
	v_mfma_f32_16x16x32_bf16 v[76:79], v[184:187], v[216:219], v[76:79]
	v_mfma_f32_16x16x32_bf16 v[72:75], v[192:195], v[216:219], v[72:75]
	v_mfma_f32_16x16x32_bf16 v[68:71], v[184:187], v[234:237], v[68:71]
	v_mfma_f32_16x16x32_bf16 v[60:63], v[192:195], v[234:237], v[60:63]
	v_mfma_f32_16x16x32_bf16 v[36:39], v[184:187], v[242:245], v[36:39]
	v_mfma_f32_16x16x32_bf16 v[28:31], v[192:195], v[242:245], v[28:31]
	v_mfma_f32_16x16x32_bf16 v[20:23], v[184:187], v[250:253], v[20:23]
	v_mfma_f32_16x16x32_bf16 v[12:15], v[192:195], v[250:253], v[12:15]
	v_mfma_f32_16x16x32_bf16 v[64:67], v[196:199], v[212:215], v[64:67]
	v_mfma_f32_16x16x32_bf16 v[56:59], v[204:207], v[212:215], v[56:59]
	v_mfma_f32_16x16x32_bf16 v[32:35], v[196:199], v[220:223], v[32:35]
	v_mfma_f32_16x16x32_bf16 v[24:27], v[204:207], v[220:223], v[24:27]
	v_mfma_f32_16x16x32_bf16 v[16:19], v[196:199], v[238:241], v[16:19]
	v_mfma_f32_16x16x32_bf16 v[8:11], v[204:207], v[238:241], v[8:11]
	v_mfma_f32_16x16x32_bf16 v[4:7], v[196:199], v[246:249], v[4:7]
	v_mfma_f32_16x16x32_bf16 v[0:3], v[204:207], v[246:249], v[0:3]
	v_mfma_f32_16x16x32_bf16 v[64:67], v[200:203], v[216:219], v[64:67]
	v_mfma_f32_16x16x32_bf16 v[56:59], v[208:211], v[216:219], v[56:59]
	v_mfma_f32_16x16x32_bf16 v[32:35], v[200:203], v[234:237], v[32:35]
	v_mfma_f32_16x16x32_bf16 v[24:27], v[208:211], v[234:237], v[24:27]
	v_mfma_f32_16x16x32_bf16 v[16:19], v[200:203], v[242:245], v[16:19]
	v_mfma_f32_16x16x32_bf16 v[8:11], v[208:211], v[242:245], v[8:11]
	v_mfma_f32_16x16x32_bf16 v[4:7], v[200:203], v[250:253], v[4:7]
	v_mfma_f32_16x16x32_bf16 v[0:3], v[208:211], v[250:253], v[0:3]
	s_barrier
	s_add_i32 s67, 0, 0x18000
	v_add_u32_e32 v163, s67, v157
	s_add_i32 s68, 0, 0x1c000
	ds_read_b128 v[180:183], v163
	ds_read_b128 v[184:187], v163 offset:1024
	ds_read_b128 v[188:191], v163 offset:2048
	ds_read_b128 v[192:195], v163 offset:3072
	v_add_u32_e32 v163, s68, v157
	ds_read_b128 v[196:199], v163
	ds_read_b128 v[200:203], v163 offset:1024
	ds_read_b128 v[204:207], v163 offset:2048
	ds_read_b128 v[208:211], v163 offset:3072
	s_add_u32 s46, s52, 0x40000
	s_addc_u32 s47, s53, 0
	s_mov_b32 m0, s56
	v_lshl_add_u64 v[230:231], s[46:47], 0, v[144:145]
	ds_read_b128 v[212:215], v161 offset:32768
	ds_read_b128 v[216:219], v161 offset:33792
	ds_read_b128 v[220:223], v161 offset:34816
	ds_read_b128 v[234:237], v161 offset:35840
	ds_read_b128 v[238:241], v161 offset:36864
	ds_read_b128 v[242:245], v161 offset:37888
	ds_read_b128 v[246:249], v161 offset:38912
	ds_read_b128 v[250:253], v161 offset:39936
	global_load_lds_dwordx4 v[230:231], off
	v_lshl_add_u64 v[230:231], s[46:47], 0, v[146:147]
	s_mov_b32 m0, s57
	s_nop 0
	global_load_lds_dwordx4 v[230:231], off
	s_waitcnt vmcnt(8)
	s_waitcnt lgkmcnt(0)
	s_barrier
	s_waitcnt lgkmcnt(0)
	v_mfma_f32_16x16x32_bf16 v[140:143], v[180:183], v[212:215], v[140:143]
	v_mfma_f32_16x16x32_bf16 v[136:139], v[188:191], v[212:215], v[136:139]
	v_mfma_f32_16x16x32_bf16 v[128:131], v[180:183], v[220:223], v[128:131]
	v_mfma_f32_16x16x32_bf16 v[120:123], v[188:191], v[220:223], v[120:123]
	v_mfma_f32_16x16x32_bf16 v[112:115], v[180:183], v[238:241], v[112:115]
	v_mfma_f32_16x16x32_bf16 v[104:107], v[188:191], v[238:241], v[104:107]
	v_mfma_f32_16x16x32_bf16 v[96:99], v[180:183], v[246:249], v[96:99]
	v_mfma_f32_16x16x32_bf16 v[88:91], v[188:191], v[246:249], v[88:91]
	v_mfma_f32_16x16x32_bf16 v[140:143], v[184:187], v[216:219], v[140:143]
	v_mfma_f32_16x16x32_bf16 v[136:139], v[192:195], v[216:219], v[136:139]
	v_mfma_f32_16x16x32_bf16 v[128:131], v[184:187], v[234:237], v[128:131]
	v_mfma_f32_16x16x32_bf16 v[120:123], v[192:195], v[234:237], v[120:123]
	v_mfma_f32_16x16x32_bf16 v[112:115], v[184:187], v[242:245], v[112:115]
	v_mfma_f32_16x16x32_bf16 v[104:107], v[192:195], v[242:245], v[104:107]
	v_mfma_f32_16x16x32_bf16 v[96:99], v[184:187], v[250:253], v[96:99]
	v_mfma_f32_16x16x32_bf16 v[88:91], v[192:195], v[250:253], v[88:91]
	v_mfma_f32_16x16x32_bf16 v[132:135], v[196:199], v[212:215], v[132:135]
	v_mfma_f32_16x16x32_bf16 v[124:127], v[204:207], v[212:215], v[124:127]
	v_mfma_f32_16x16x32_bf16 v[116:119], v[196:199], v[220:223], v[116:119]
	v_mfma_f32_16x16x32_bf16 v[108:111], v[204:207], v[220:223], v[108:111]
	v_mfma_f32_16x16x32_bf16 v[100:103], v[196:199], v[238:241], v[100:103]
	v_mfma_f32_16x16x32_bf16 v[92:95], v[204:207], v[238:241], v[92:95]
	v_mfma_f32_16x16x32_bf16 v[84:87], v[196:199], v[246:249], v[84:87]
	v_mfma_f32_16x16x32_bf16 v[80:83], v[204:207], v[246:249], v[80:83]
	v_mfma_f32_16x16x32_bf16 v[132:135], v[200:203], v[216:219], v[132:135]
	v_mfma_f32_16x16x32_bf16 v[124:127], v[208:211], v[216:219], v[124:127]
	v_mfma_f32_16x16x32_bf16 v[116:119], v[200:203], v[234:237], v[116:119]
	v_mfma_f32_16x16x32_bf16 v[108:111], v[208:211], v[234:237], v[108:111]
	v_mfma_f32_16x16x32_bf16 v[100:103], v[200:203], v[242:245], v[100:103]
	v_mfma_f32_16x16x32_bf16 v[92:95], v[208:211], v[242:245], v[92:95]
	v_mfma_f32_16x16x32_bf16 v[84:87], v[200:203], v[250:253], v[84:87]
	v_mfma_f32_16x16x32_bf16 v[80:83], v[208:211], v[250:253], v[80:83]
	s_barrier
	s_add_i32 s46, s67, s43
	v_lshl_add_u64 v[170:171], v[170:171], 0, s[36:37]
	s_mov_b32 m0, s46
	ds_read_b128 v[212:215], v161 offset:49152
	ds_read_b128 v[216:219], v161 offset:50176
	ds_read_b128 v[220:223], v161 offset:51200
	ds_read_b128 v[234:237], v161 offset:52224
	ds_read_b128 v[238:241], v161 offset:53248
	ds_read_b128 v[242:245], v161 offset:54272
	ds_read_b128 v[246:249], v161 offset:55296
	ds_read_b128 v[250:253], v161 offset:56320
	global_load_lds_dwordx4 v[170:171], off
	s_add_i32 m0, s46, 0x2000
	s_add_u32 s46, s50, 0x40080
	v_lshl_add_u64 v[170:171], v[172:173], 0, s[36:37]
	s_addc_u32 s47, s51, 0
	s_add_i32 s50, s68, s43
	global_load_lds_dwordx4 v[170:171], off
	v_lshl_add_u64 v[170:171], s[46:47], 0, v[168:169]
	s_mov_b32 m0, s50
	s_nop 0
	global_load_lds_dwordx4 v[170:171], off
	v_lshl_add_u64 v[170:171], s[46:47], 0, v[148:149]
	s_add_i32 m0, s50, 0x2000
	s_nop 0
	global_load_lds_dwordx4 v[170:171], off
	v_lshl_add_u64 v[170:171], v[224:225], 0, s[36:37]
	s_mov_b32 m0, s59
	s_nop 0
	global_load_lds_dwordx4 v[170:171], off
	v_lshl_add_u64 v[170:171], v[228:229], 0, s[36:37]
	s_mov_b32 m0, s60
	s_nop 0
	global_load_lds_dwordx4 v[170:171], off
	s_waitcnt vmcnt(8)
	s_waitcnt lgkmcnt(0)
	s_barrier
	s_waitcnt lgkmcnt(0)
	v_mfma_f32_16x16x32_bf16 v[76:79], v[180:183], v[212:215], v[76:79]
	v_mfma_f32_16x16x32_bf16 v[72:75], v[188:191], v[212:215], v[72:75]
	v_mfma_f32_16x16x32_bf16 v[68:71], v[180:183], v[220:223], v[68:71]
	v_mfma_f32_16x16x32_bf16 v[60:63], v[188:191], v[220:223], v[60:63]
	v_mfma_f32_16x16x32_bf16 v[36:39], v[180:183], v[238:241], v[36:39]
	v_mfma_f32_16x16x32_bf16 v[28:31], v[188:191], v[238:241], v[28:31]
	v_mfma_f32_16x16x32_bf16 v[20:23], v[180:183], v[246:249], v[20:23]
	v_mfma_f32_16x16x32_bf16 v[12:15], v[188:191], v[246:249], v[12:15]
	v_mfma_f32_16x16x32_bf16 v[76:79], v[184:187], v[216:219], v[76:79]
	v_mfma_f32_16x16x32_bf16 v[72:75], v[192:195], v[216:219], v[72:75]
	v_mfma_f32_16x16x32_bf16 v[68:71], v[184:187], v[234:237], v[68:71]
	v_mfma_f32_16x16x32_bf16 v[60:63], v[192:195], v[234:237], v[60:63]
	v_mfma_f32_16x16x32_bf16 v[36:39], v[184:187], v[242:245], v[36:39]
	v_mfma_f32_16x16x32_bf16 v[28:31], v[192:195], v[242:245], v[28:31]
	v_mfma_f32_16x16x32_bf16 v[20:23], v[184:187], v[250:253], v[20:23]
	v_mfma_f32_16x16x32_bf16 v[12:15], v[192:195], v[250:253], v[12:15]
	v_mfma_f32_16x16x32_bf16 v[64:67], v[196:199], v[212:215], v[64:67]
	v_mfma_f32_16x16x32_bf16 v[56:59], v[204:207], v[212:215], v[56:59]
	v_mfma_f32_16x16x32_bf16 v[32:35], v[196:199], v[220:223], v[32:35]
	v_mfma_f32_16x16x32_bf16 v[24:27], v[204:207], v[220:223], v[24:27]
	v_mfma_f32_16x16x32_bf16 v[16:19], v[196:199], v[238:241], v[16:19]
	v_mfma_f32_16x16x32_bf16 v[8:11], v[204:207], v[238:241], v[8:11]
	v_mfma_f32_16x16x32_bf16 v[4:7], v[196:199], v[246:249], v[4:7]
	v_mfma_f32_16x16x32_bf16 v[0:3], v[204:207], v[246:249], v[0:3]
	v_mfma_f32_16x16x32_bf16 v[64:67], v[200:203], v[216:219], v[64:67]
	v_mfma_f32_16x16x32_bf16 v[56:59], v[208:211], v[216:219], v[56:59]
	v_mfma_f32_16x16x32_bf16 v[32:35], v[200:203], v[234:237], v[32:35]
	v_mfma_f32_16x16x32_bf16 v[24:27], v[208:211], v[234:237], v[24:27]
	v_mfma_f32_16x16x32_bf16 v[16:19], v[200:203], v[242:245], v[16:19]
	v_mfma_f32_16x16x32_bf16 v[8:11], v[208:211], v[242:245], v[8:11]
	v_mfma_f32_16x16x32_bf16 v[4:7], v[200:203], v[250:253], v[4:7]
	v_mfma_f32_16x16x32_bf16 v[0:3], v[208:211], v[250:253], v[0:3]
	s_barrier
	s_add_i32 s66, s66, 2
	s_add_u32 s64, s64, 0x100
	s_addc_u32 s65, s65, 0
	s_add_u32 s48, s48, 0x100
	s_addc_u32 s49, s49, 0
	s_cmp_gt_u32 s66, 13
	s_cbranch_scc0 .LBB0_256
	s_and_b64 vcc, exec, s[14:15]
	s_cbranch_vccz .LBB0_259
	s_barrier

.LBB0_348:
	s_add_u32 s46, s58, 0xfffc0080
	s_addc_u32 s47, s59, -1
	s_add_i32 s82, 0, 0x10000
	s_cmp_eq_u32 s84, 12
	s_cselect_b32 s63, s53, s47
	s_cselect_b32 s62, s77, s46
	v_add_u32_e32 v159, s82, v162
	s_cselect_b32 s61, s51, s90
	s_cselect_b32 s60, s83, s89
	s_add_i32 s91, 0, 0x14000
	ds_read_b128 v[178:181], v159
	ds_read_b128 v[182:185], v159 offset:1024
	ds_read_b128 v[186:189], v159 offset:2048
	ds_read_b128 v[190:193], v159 offset:3072
	v_add_u32_e32 v159, s91, v162
	ds_read_b128 v[194:197], v159
	ds_read_b128 v[198:201], v159 offset:1024
	ds_read_b128 v[202:205], v159 offset:2048
	ds_read_b128 v[206:209], v159 offset:3072
	v_lshl_add_u64 v[250:251], s[58:59], 0, v[152:153]
	s_add_i32 m0, s67, 0xc000
	ds_read_b128 v[210:213], v164
	ds_read_b128 v[214:217], v164 offset:1024
	ds_read_b128 v[218:221], v164 offset:2048
	ds_read_b128 v[222:225], v164 offset:3072
	ds_read_b128 v[234:237], v164 offset:4096
	ds_read_b128 v[238:241], v164 offset:5120
	ds_read_b128 v[242:245], v164 offset:6144
	ds_read_b128 v[246:249], v164 offset:7168
	global_load_lds_dwordx4 v[250:251], off
	v_lshl_add_u64 v[250:251], s[58:59], 0, v[150:151]
	s_add_i32 m0, s67, 0xe000
	s_nop 0
	global_load_lds_dwordx4 v[250:251], off
	s_waitcnt vmcnt(8)
	s_waitcnt lgkmcnt(0)
	s_barrier
	s_waitcnt lgkmcnt(0)
	v_mfma_f32_16x16x32_bf16 v[140:143], v[178:181], v[210:213], v[140:143]
	v_mfma_f32_16x16x32_bf16 v[136:139], v[186:189], v[210:213], v[136:139]
	v_mfma_f32_16x16x32_bf16 v[128:131], v[178:181], v[218:221], v[128:131]
	v_mfma_f32_16x16x32_bf16 v[124:127], v[186:189], v[218:221], v[124:127]
	v_mfma_f32_16x16x32_bf16 v[116:119], v[178:181], v[234:237], v[116:119]
	v_mfma_f32_16x16x32_bf16 v[108:111], v[186:189], v[234:237], v[108:111]
	v_mfma_f32_16x16x32_bf16 v[100:103], v[178:181], v[242:245], v[100:103]
	v_mfma_f32_16x16x32_bf16 v[92:95], v[186:189], v[242:245], v[92:95]
	v_mfma_f32_16x16x32_bf16 v[140:143], v[182:185], v[214:217], v[140:143]
	v_mfma_f32_16x16x32_bf16 v[136:139], v[190:193], v[214:217], v[136:139]
	v_mfma_f32_16x16x32_bf16 v[128:131], v[182:185], v[222:225], v[128:131]
	v_mfma_f32_16x16x32_bf16 v[124:127], v[190:193], v[222:225], v[124:127]
	v_mfma_f32_16x16x32_bf16 v[116:119], v[182:185], v[238:241], v[116:119]
	v_mfma_f32_16x16x32_bf16 v[108:111], v[190:193], v[238:241], v[108:111]
	v_mfma_f32_16x16x32_bf16 v[100:103], v[182:185], v[246:249], v[100:103]
	v_mfma_f32_16x16x32_bf16 v[92:95], v[190:193], v[246:249], v[92:95]
	v_mfma_f32_16x16x32_bf16 v[132:135], v[194:197], v[210:213], v[132:135]
	v_mfma_f32_16x16x32_bf16 v[120:123], v[202:205], v[210:213], v[120:123]
	v_mfma_f32_16x16x32_bf16 v[112:115], v[194:197], v[218:221], v[112:115]
	v_mfma_f32_16x16x32_bf16 v[104:107], v[202:205], v[218:221], v[104:107]
	v_mfma_f32_16x16x32_bf16 v[96:99], v[194:197], v[234:237], v[96:99]
	v_mfma_f32_16x16x32_bf16 v[88:91], v[202:205], v[234:237], v[88:91]
	v_mfma_f32_16x16x32_bf16 v[84:87], v[194:197], v[242:245], v[84:87]
	v_mfma_f32_16x16x32_bf16 v[80:83], v[202:205], v[242:245], v[80:83]
	v_mfma_f32_16x16x32_bf16 v[132:135], v[198:201], v[214:217], v[132:135]
	v_mfma_f32_16x16x32_bf16 v[120:123], v[206:209], v[214:217], v[120:123]
	v_mfma_f32_16x16x32_bf16 v[112:115], v[198:201], v[222:225], v[112:115]
	v_mfma_f32_16x16x32_bf16 v[104:107], v[206:209], v[222:225], v[104:107]
	v_mfma_f32_16x16x32_bf16 v[96:99], v[198:201], v[238:241], v[96:99]
	v_mfma_f32_16x16x32_bf16 v[88:91], v[206:209], v[238:241], v[88:91]
	v_mfma_f32_16x16x32_bf16 v[84:87], v[198:201], v[246:249], v[84:87]
	v_mfma_f32_16x16x32_bf16 v[80:83], v[206:209], v[246:249], v[80:83]
	s_barrier
	s_add_i32 s46, s82, s65
	v_lshl_add_u64 v[250:251], s[60:61], 0, v[168:169]
	s_mov_b32 m0, s46
	ds_read_b128 v[210:213], v164 offset:16384
	ds_read_b128 v[214:217], v164 offset:17408
	ds_read_b128 v[218:221], v164 offset:18432
	ds_read_b128 v[222:225], v164 offset:19456
	ds_read_b128 v[234:237], v164 offset:20480
	ds_read_b128 v[238:241], v164 offset:21504
	ds_read_b128 v[242:245], v164 offset:22528
	ds_read_b128 v[246:249], v164 offset:23552
	global_load_lds_dwordx4 v[250:251], off
	s_add_i32 m0, s46, 0x2000
	s_add_u32 s46, s60, 0x40000
	v_lshl_add_u64 v[252:253], s[60:61], 0, v[144:145]
	s_addc_u32 s47, s61, 0
	s_add_i32 s82, s91, s65
	global_load_lds_dwordx4 v[252:253], off
	v_lshl_add_u64 v[228:229], s[46:47], 0, v[168:169]
	s_mov_b32 m0, s82
	v_lshl_add_u64 v[170:171], s[62:63], 0, v[146:147]
	global_load_lds_dwordx4 v[228:229], off
	v_lshl_add_u64 v[228:229], s[46:47], 0, v[144:145]
	s_add_i32 m0, s82, 0x2000
	s_nop 0
	global_load_lds_dwordx4 v[228:229], off
	v_lshl_add_u64 v[228:229], s[62:63], 0, v[148:149]
	s_mov_b32 m0, s67
	s_nop 0
	global_load_lds_dwordx4 v[228:229], off
	s_mov_b32 m0, s68
	s_nop 0
	global_load_lds_dwordx4 v[170:171], off
	s_waitcnt vmcnt(8)
	s_waitcnt lgkmcnt(0)
	s_barrier
	s_waitcnt lgkmcnt(0)
	v_mfma_f32_16x16x32_bf16 v[76:79], v[178:181], v[210:213], v[76:79]
	v_mfma_f32_16x16x32_bf16 v[72:75], v[186:189], v[210:213], v[72:75]
	v_mfma_f32_16x16x32_bf16 v[68:71], v[178:181], v[218:221], v[68:71]
	v_mfma_f32_16x16x32_bf16 v[60:63], v[186:189], v[218:221], v[60:63]
	v_mfma_f32_16x16x32_bf16 v[52:55], v[178:181], v[234:237], v[52:55]
	v_mfma_f32_16x16x32_bf16 v[44:47], v[186:189], v[234:237], v[44:47]
	v_mfma_f32_16x16x32_bf16 v[36:39], v[178:181], v[242:245], v[36:39]
	v_mfma_f32_16x16x32_bf16 v[28:31], v[186:189], v[242:245], v[28:31]
	v_mfma_f32_16x16x32_bf16 v[76:79], v[182:185], v[214:217], v[76:79]
	v_mfma_f32_16x16x32_bf16 v[72:75], v[190:193], v[214:217], v[72:75]
	v_mfma_f32_16x16x32_bf16 v[68:71], v[182:185], v[222:225], v[68:71]
	v_mfma_f32_16x16x32_bf16 v[60:63], v[190:193], v[222:225], v[60:63]
	v_mfma_f32_16x16x32_bf16 v[52:55], v[182:185], v[238:241], v[52:55]
	v_mfma_f32_16x16x32_bf16 v[44:47], v[190:193], v[238:241], v[44:47]
	v_mfma_f32_16x16x32_bf16 v[36:39], v[182:185], v[246:249], v[36:39]
	v_mfma_f32_16x16x32_bf16 v[28:31], v[190:193], v[246:249], v[28:31]
	v_mfma_f32_16x16x32_bf16 v[64:67], v[194:197], v[210:213], v[64:67]
	v_mfma_f32_16x16x32_bf16 v[56:59], v[202:205], v[210:213], v[56:59]
	v_mfma_f32_16x16x32_bf16 v[48:51], v[194:197], v[218:221], v[48:51]
	v_mfma_f32_16x16x32_bf16 v[40:43], v[202:205], v[218:221], v[40:43]
	v_mfma_f32_16x16x32_bf16 v[32:35], v[194:197], v[234:237], v[32:35]
	v_mfma_f32_16x16x32_bf16 v[24:27], v[202:205], v[234:237], v[24:27]
	v_mfma_f32_16x16x32_bf16 v[20:23], v[194:197], v[242:245], v[20:23]
	v_mfma_f32_16x16x32_bf16 v[16:19], v[202:205], v[242:245], v[16:19]
	v_mfma_f32_16x16x32_bf16 v[64:67], v[198:201], v[214:217], v[64:67]
	v_mfma_f32_16x16x32_bf16 v[56:59], v[206:209], v[214:217], v[56:59]
	v_mfma_f32_16x16x32_bf16 v[48:51], v[198:201], v[222:225], v[48:51]
	v_mfma_f32_16x16x32_bf16 v[40:43], v[206:209], v[222:225], v[40:43]
	v_mfma_f32_16x16x32_bf16 v[32:35], v[198:201], v[238:241], v[32:35]
	v_mfma_f32_16x16x32_bf16 v[24:27], v[206:209], v[238:241], v[24:27]
	v_mfma_f32_16x16x32_bf16 v[20:23], v[198:201], v[246:249], v[20:23]
	v_mfma_f32_16x16x32_bf16 v[16:19], v[206:209], v[246:249], v[16:19]
	s_barrier
	s_add_i32 s82, 0, 0x18000
	v_add_u32_e32 v159, s82, v162
	s_add_i32 s91, 0, 0x1c000
	ds_read_b128 v[178:181], v159
	ds_read_b128 v[182:185], v159 offset:1024
	ds_read_b128 v[186:189], v159 offset:2048
	ds_read_b128 v[190:193], v159 offset:3072
	v_add_u32_e32 v159, s91, v162
	ds_read_b128 v[194:197], v159
	ds_read_b128 v[198:201], v159 offset:1024
	ds_read_b128 v[202:205], v159 offset:2048
	ds_read_b128 v[206:209], v159 offset:3072
	s_add_u32 s46, s62, 0x40000
	s_addc_u32 s47, s63, 0
	s_mov_b32 m0, s69
	v_lshl_add_u64 v[172:173], s[46:47], 0, v[148:149]
	ds_read_b128 v[210:213], v164 offset:32768
	ds_read_b128 v[214:217], v164 offset:33792
	ds_read_b128 v[218:221], v164 offset:34816
	ds_read_b128 v[222:225], v164 offset:35840
	ds_read_b128 v[234:237], v164 offset:36864
	ds_read_b128 v[238:241], v164 offset:37888
	ds_read_b128 v[242:245], v164 offset:38912
	ds_read_b128 v[246:249], v164 offset:39936
	global_load_lds_dwordx4 v[172:173], off
	v_lshl_add_u64 v[172:173], s[46:47], 0, v[146:147]
	s_mov_b32 m0, s70
	s_nop 0
	global_load_lds_dwordx4 v[172:173], off
	s_waitcnt vmcnt(8)
	s_waitcnt lgkmcnt(0)
	s_barrier
	s_waitcnt lgkmcnt(0)
	v_mfma_f32_16x16x32_bf16 v[140:143], v[178:181], v[210:213], v[140:143]
	v_mfma_f32_16x16x32_bf16 v[136:139], v[186:189], v[210:213], v[136:139]
	v_mfma_f32_16x16x32_bf16 v[128:131], v[178:181], v[218:221], v[128:131]
	v_mfma_f32_16x16x32_bf16 v[124:127], v[186:189], v[218:221], v[124:127]
	v_mfma_f32_16x16x32_bf16 v[116:119], v[178:181], v[234:237], v[116:119]
	v_mfma_f32_16x16x32_bf16 v[108:111], v[186:189], v[234:237], v[108:111]
	v_mfma_f32_16x16x32_bf16 v[100:103], v[178:181], v[242:245], v[100:103]
	v_mfma_f32_16x16x32_bf16 v[92:95], v[186:189], v[242:245], v[92:95]
	v_mfma_f32_16x16x32_bf16 v[140:143], v[182:185], v[214:217], v[140:143]
	v_mfma_f32_16x16x32_bf16 v[136:139], v[190:193], v[214:217], v[136:139]
	v_mfma_f32_16x16x32_bf16 v[128:131], v[182:185], v[222:225], v[128:131]
	v_mfma_f32_16x16x32_bf16 v[124:127], v[190:193], v[222:225], v[124:127]
	v_mfma_f32_16x16x32_bf16 v[116:119], v[182:185], v[238:241], v[116:119]
	v_mfma_f32_16x16x32_bf16 v[108:111], v[190:193], v[238:241], v[108:111]
	v_mfma_f32_16x16x32_bf16 v[100:103], v[182:185], v[246:249], v[100:103]
	v_mfma_f32_16x16x32_bf16 v[92:95], v[190:193], v[246:249], v[92:95]
	v_mfma_f32_16x16x32_bf16 v[132:135], v[194:197], v[210:213], v[132:135]
	v_mfma_f32_16x16x32_bf16 v[120:123], v[202:205], v[210:213], v[120:123]
	v_mfma_f32_16x16x32_bf16 v[112:115], v[194:197], v[218:221], v[112:115]
	v_mfma_f32_16x16x32_bf16 v[104:107], v[202:205], v[218:221], v[104:107]
	v_mfma_f32_16x16x32_bf16 v[96:99], v[194:197], v[234:237], v[96:99]
	v_mfma_f32_16x16x32_bf16 v[88:91], v[202:205], v[234:237], v[88:91]
	v_mfma_f32_16x16x32_bf16 v[84:87], v[194:197], v[242:245], v[84:87]
	v_mfma_f32_16x16x32_bf16 v[80:83], v[202:205], v[242:245], v[80:83]
	v_mfma_f32_16x16x32_bf16 v[132:135], v[198:201], v[214:217], v[132:135]
	v_mfma_f32_16x16x32_bf16 v[120:123], v[206:209], v[214:217], v[120:123]
	v_mfma_f32_16x16x32_bf16 v[112:115], v[198:201], v[222:225], v[112:115]
	v_mfma_f32_16x16x32_bf16 v[104:107], v[206:209], v[222:225], v[104:107]
	v_mfma_f32_16x16x32_bf16 v[96:99], v[198:201], v[238:241], v[96:99]
	v_mfma_f32_16x16x32_bf16 v[88:91], v[206:209], v[238:241], v[88:91]
	v_mfma_f32_16x16x32_bf16 v[84:87], v[198:201], v[246:249], v[84:87]
	v_mfma_f32_16x16x32_bf16 v[80:83], v[206:209], v[246:249], v[80:83]
	s_barrier
	s_add_i32 s46, s82, s65
	v_lshl_add_u64 v[172:173], v[250:251], 0, s[36:37]
	s_mov_b32 m0, s46
	ds_read_b128 v[210:213], v164 offset:49152
	ds_read_b128 v[214:217], v164 offset:50176
	ds_read_b128 v[218:221], v164 offset:51200
	ds_read_b128 v[222:225], v164 offset:52224
	ds_read_b128 v[234:237], v164 offset:53248
	ds_read_b128 v[238:241], v164 offset:54272
	ds_read_b128 v[242:245], v164 offset:55296
	ds_read_b128 v[246:249], v164 offset:56320
	global_load_lds_dwordx4 v[172:173], off
	s_add_i32 m0, s46, 0x2000
	s_add_u32 s46, s60, 0x40080
	v_lshl_add_u64 v[172:173], v[252:253], 0, s[36:37]
	s_addc_u32 s47, s61, 0
	s_add_i32 s60, s91, s65
	global_load_lds_dwordx4 v[172:173], off
	v_lshl_add_u64 v[172:173], s[46:47], 0, v[168:169]
	s_mov_b32 m0, s60
	v_lshl_add_u64 v[170:171], v[170:171], 0, s[36:37]
	global_load_lds_dwordx4 v[172:173], off
	v_lshl_add_u64 v[172:173], s[46:47], 0, v[144:145]
	s_add_i32 m0, s60, 0x2000
	s_nop 0
	global_load_lds_dwordx4 v[172:173], off
	v_lshl_add_u64 v[172:173], v[228:229], 0, s[36:37]
	s_mov_b32 m0, s73
	s_nop 0
	global_load_lds_dwordx4 v[172:173], off
	s_mov_b32 m0, s78
	s_nop 0
	global_load_lds_dwordx4 v[170:171], off
	s_waitcnt vmcnt(8)
	s_waitcnt lgkmcnt(0)
	s_barrier
	s_waitcnt lgkmcnt(0)
	v_mfma_f32_16x16x32_bf16 v[76:79], v[178:181], v[210:213], v[76:79]
	v_mfma_f32_16x16x32_bf16 v[72:75], v[186:189], v[210:213], v[72:75]
	v_mfma_f32_16x16x32_bf16 v[68:71], v[178:181], v[218:221], v[68:71]
	v_mfma_f32_16x16x32_bf16 v[60:63], v[186:189], v[218:221], v[60:63]
	v_mfma_f32_16x16x32_bf16 v[52:55], v[178:181], v[234:237], v[52:55]
	v_mfma_f32_16x16x32_bf16 v[44:47], v[186:189], v[234:237], v[44:47]
	v_mfma_f32_16x16x32_bf16 v[36:39], v[178:181], v[242:245], v[36:39]
	v_mfma_f32_16x16x32_bf16 v[28:31], v[186:189], v[242:245], v[28:31]
	v_mfma_f32_16x16x32_bf16 v[76:79], v[182:185], v[214:217], v[76:79]
	v_mfma_f32_16x16x32_bf16 v[72:75], v[190:193], v[214:217], v[72:75]
	v_mfma_f32_16x16x32_bf16 v[68:71], v[182:185], v[222:225], v[68:71]
	v_mfma_f32_16x16x32_bf16 v[60:63], v[190:193], v[222:225], v[60:63]
	v_mfma_f32_16x16x32_bf16 v[52:55], v[182:185], v[238:241], v[52:55]
	v_mfma_f32_16x16x32_bf16 v[44:47], v[190:193], v[238:241], v[44:47]
	v_mfma_f32_16x16x32_bf16 v[36:39], v[182:185], v[246:249], v[36:39]
	v_mfma_f32_16x16x32_bf16 v[28:31], v[190:193], v[246:249], v[28:31]
	v_mfma_f32_16x16x32_bf16 v[64:67], v[194:197], v[210:213], v[64:67]
	v_mfma_f32_16x16x32_bf16 v[56:59], v[202:205], v[210:213], v[56:59]
	v_mfma_f32_16x16x32_bf16 v[48:51], v[194:197], v[218:221], v[48:51]
	v_mfma_f32_16x16x32_bf16 v[40:43], v[202:205], v[218:221], v[40:43]
	v_mfma_f32_16x16x32_bf16 v[32:35], v[194:197], v[234:237], v[32:35]
	v_mfma_f32_16x16x32_bf16 v[24:27], v[202:205], v[234:237], v[24:27]
	v_mfma_f32_16x16x32_bf16 v[20:23], v[194:197], v[242:245], v[20:23]
	v_mfma_f32_16x16x32_bf16 v[16:19], v[202:205], v[242:245], v[16:19]
	v_mfma_f32_16x16x32_bf16 v[64:67], v[198:201], v[214:217], v[64:67]
	v_mfma_f32_16x16x32_bf16 v[56:59], v[206:209], v[214:217], v[56:59]
	v_mfma_f32_16x16x32_bf16 v[48:51], v[198:201], v[222:225], v[48:51]
	v_mfma_f32_16x16x32_bf16 v[40:43], v[206:209], v[222:225], v[40:43]
	v_mfma_f32_16x16x32_bf16 v[32:35], v[198:201], v[238:241], v[32:35]
	v_mfma_f32_16x16x32_bf16 v[24:27], v[206:209], v[238:241], v[24:27]
	v_mfma_f32_16x16x32_bf16 v[20:23], v[198:201], v[246:249], v[20:23]
	v_mfma_f32_16x16x32_bf16 v[16:19], v[206:209], v[246:249], v[16:19]
	s_barrier
	s_add_i32 s84, s84, 2
	s_add_u32 s89, s89, 0x100
	s_addc_u32 s90, s90, 0
	s_add_u32 s58, s58, 0x100
	s_addc_u32 s59, s59, 0
	s_cmp_gt_u32 s84, 13
	s_cbranch_scc0 .LBB0_348
	s_and_b64 vcc, exec, s[48:49]
	s_cbranch_vccz .LBB0_351
	s_barrier

.LBB0_654:
	s_add_u32 s46, s58, 0xfffc0080
	s_addc_u32 s47, s59, -1
	s_add_i32 s82, 0, 0x10000
	s_cmp_eq_u32 s84, 12
	s_cselect_b32 s63, s31, s47
	s_cselect_b32 s62, s51, s46
	s_cselect_b32 s61, s49, s79
	s_cselect_b32 s60, s57, s77
	s_add_i32 s83, 0, 0x14000
	v_add_u32_e32 v52, s82, v209
	v_add_u32_e32 v156, s83, v209
	ds_read_b128 v[32:35], v52
	ds_read_b128 v[36:39], v52 offset:1024
	ds_read_b128 v[48:51], v52 offset:2048
	ds_read_b128 v[52:55], v52 offset:3072
	ds_read_b128 v[144:147], v156
	ds_read_b128 v[148:151], v156 offset:1024
	ds_read_b128 v[152:155], v156 offset:2048
	ds_read_b128 v[156:159], v156 offset:3072
	v_lshl_add_u64 v[170:171], s[58:59], 0, v[182:183]
	s_add_i32 m0, s71, 0xc000
	ds_read_b128 v[160:163], v211
	ds_read_b128 v[164:167], v211 offset:1024
	ds_read_b128 v[184:187], v211 offset:2048
	ds_read_b128 v[188:191], v211 offset:3072
	ds_read_b128 v[192:195], v211 offset:4096
	ds_read_b128 v[196:199], v211 offset:5120
	ds_read_b128 v[200:203], v211 offset:6144
	ds_read_b128 v[204:207], v211 offset:7168
	global_load_lds_dwordx4 v[170:171], off
	v_lshl_add_u64 v[170:171], s[58:59], 0, v[180:181]
	s_add_i32 m0, s71, 0xe000
	s_nop 0
	global_load_lds_dwordx4 v[170:171], off
	s_waitcnt vmcnt(8)
	s_waitcnt lgkmcnt(0)
	s_barrier
	s_waitcnt lgkmcnt(0)
	v_mfma_f32_16x16x32_bf16 v[140:143], v[32:35], v[160:163], v[140:143]
	v_mfma_f32_16x16x32_bf16 v[136:139], v[48:51], v[160:163], v[136:139]
	v_mfma_f32_16x16x32_bf16 v[124:127], v[32:35], v[184:187], v[124:127]
	v_mfma_f32_16x16x32_bf16 v[120:123], v[48:51], v[184:187], v[120:123]
	v_mfma_f32_16x16x32_bf16 v[108:111], v[32:35], v[192:195], v[108:111]
	v_mfma_f32_16x16x32_bf16 v[104:107], v[48:51], v[192:195], v[104:107]
	v_mfma_f32_16x16x32_bf16 v[92:95], v[32:35], v[200:203], v[92:95]
	v_mfma_f32_16x16x32_bf16 v[88:91], v[48:51], v[200:203], v[88:91]
	v_mfma_f32_16x16x32_bf16 v[140:143], v[36:39], v[164:167], v[140:143]
	v_mfma_f32_16x16x32_bf16 v[136:139], v[52:55], v[164:167], v[136:139]
	v_mfma_f32_16x16x32_bf16 v[124:127], v[36:39], v[188:191], v[124:127]
	v_mfma_f32_16x16x32_bf16 v[120:123], v[52:55], v[188:191], v[120:123]
	v_mfma_f32_16x16x32_bf16 v[108:111], v[36:39], v[196:199], v[108:111]
	v_mfma_f32_16x16x32_bf16 v[104:107], v[52:55], v[196:199], v[104:107]
	v_mfma_f32_16x16x32_bf16 v[92:95], v[36:39], v[204:207], v[92:95]
	v_mfma_f32_16x16x32_bf16 v[88:91], v[52:55], v[204:207], v[88:91]
	v_mfma_f32_16x16x32_bf16 v[132:135], v[144:147], v[160:163], v[132:135]
	v_mfma_f32_16x16x32_bf16 v[128:131], v[152:155], v[160:163], v[128:131]
	v_mfma_f32_16x16x32_bf16 v[116:119], v[144:147], v[184:187], v[116:119]
	v_mfma_f32_16x16x32_bf16 v[112:115], v[152:155], v[184:187], v[112:115]
	v_mfma_f32_16x16x32_bf16 v[100:103], v[144:147], v[192:195], v[100:103]
	v_mfma_f32_16x16x32_bf16 v[96:99], v[152:155], v[192:195], v[96:99]
	v_mfma_f32_16x16x32_bf16 v[84:87], v[144:147], v[200:203], v[84:87]
	v_mfma_f32_16x16x32_bf16 v[80:83], v[152:155], v[200:203], v[80:83]
	v_mfma_f32_16x16x32_bf16 v[132:135], v[148:151], v[164:167], v[132:135]
	v_mfma_f32_16x16x32_bf16 v[128:131], v[156:159], v[164:167], v[128:131]
	v_mfma_f32_16x16x32_bf16 v[116:119], v[148:151], v[188:191], v[116:119]
	v_mfma_f32_16x16x32_bf16 v[112:115], v[156:159], v[188:191], v[112:115]
	v_mfma_f32_16x16x32_bf16 v[100:103], v[148:151], v[196:199], v[100:103]
	v_mfma_f32_16x16x32_bf16 v[96:99], v[156:159], v[196:199], v[96:99]
	v_mfma_f32_16x16x32_bf16 v[84:87], v[148:151], v[204:207], v[84:87]
	v_mfma_f32_16x16x32_bf16 v[80:83], v[156:159], v[204:207], v[80:83]
	s_barrier
	s_add_i32 s46, s82, s70
	v_lshl_add_u64 v[170:171], s[60:61], 0, v[168:169]
	s_mov_b32 m0, s46
	ds_read_b128 v[160:163], v211 offset:16384
	ds_read_b128 v[164:167], v211 offset:17408
	ds_read_b128 v[184:187], v211 offset:18432
	ds_read_b128 v[188:191], v211 offset:19456
	ds_read_b128 v[192:195], v211 offset:20480
	ds_read_b128 v[196:199], v211 offset:21504
	ds_read_b128 v[200:203], v211 offset:22528
	ds_read_b128 v[204:207], v211 offset:23552
	global_load_lds_dwordx4 v[170:171], off
	s_add_i32 m0, s46, 0x2000
	s_add_u32 s46, s60, 0x40000
	v_lshl_add_u64 v[172:173], s[60:61], 0, v[178:179]
	s_addc_u32 s47, s61, 0
	s_add_i32 s82, s83, s70
	global_load_lds_dwordx4 v[172:173], off
	v_lshl_add_u64 v[212:213], s[46:47], 0, v[168:169]
	s_mov_b32 m0, s82
	v_lshl_add_u64 v[214:215], s[62:63], 0, v[176:177]
	global_load_lds_dwordx4 v[212:213], off
	v_lshl_add_u64 v[212:213], s[46:47], 0, v[178:179]
	s_add_i32 m0, s82, 0x2000
	s_nop 0
	global_load_lds_dwordx4 v[212:213], off
	v_lshl_add_u64 v[212:213], s[62:63], 0, v[174:175]
	s_mov_b32 m0, s71
	s_nop 0
	global_load_lds_dwordx4 v[212:213], off
	s_mov_b32 m0, s72
	s_nop 0
	global_load_lds_dwordx4 v[214:215], off
	s_waitcnt vmcnt(8)
	s_waitcnt lgkmcnt(0)
	s_barrier
	s_waitcnt lgkmcnt(0)
	v_mfma_f32_16x16x32_bf16 v[76:79], v[32:35], v[160:163], v[76:79]
	v_mfma_f32_16x16x32_bf16 v[72:75], v[48:51], v[160:163], v[72:75]
	v_mfma_f32_16x16x32_bf16 v[60:63], v[32:35], v[184:187], v[60:63]
	v_mfma_f32_16x16x32_bf16 v[56:59], v[48:51], v[184:187], v[56:59]
	v_mfma_f32_16x16x32_bf16 v[28:31], v[32:35], v[192:195], v[28:31]
	v_mfma_f32_16x16x32_bf16 v[24:27], v[48:51], v[192:195], v[24:27]
	v_mfma_f32_16x16x32_bf16 v[12:15], v[32:35], v[200:203], v[12:15]
	v_mfma_f32_16x16x32_bf16 v[8:11], v[48:51], v[200:203], v[8:11]
	v_mfma_f32_16x16x32_bf16 v[76:79], v[36:39], v[164:167], v[76:79]
	v_mfma_f32_16x16x32_bf16 v[72:75], v[52:55], v[164:167], v[72:75]
	v_mfma_f32_16x16x32_bf16 v[60:63], v[36:39], v[188:191], v[60:63]
	v_mfma_f32_16x16x32_bf16 v[56:59], v[52:55], v[188:191], v[56:59]
	v_mfma_f32_16x16x32_bf16 v[28:31], v[36:39], v[196:199], v[28:31]
	v_mfma_f32_16x16x32_bf16 v[24:27], v[52:55], v[196:199], v[24:27]
	v_mfma_f32_16x16x32_bf16 v[12:15], v[36:39], v[204:207], v[12:15]
	v_mfma_f32_16x16x32_bf16 v[8:11], v[52:55], v[204:207], v[8:11]
	v_mfma_f32_16x16x32_bf16 v[44:47], v[144:147], v[184:187], v[44:47]
	v_mfma_f32_16x16x32_bf16 v[40:43], v[152:155], v[184:187], v[40:43]
	v_mfma_f32_16x16x32_bf16 v[20:23], v[144:147], v[192:195], v[20:23]
	v_mfma_f32_16x16x32_bf16 v[16:19], v[152:155], v[192:195], v[16:19]
	v_mfma_f32_16x16x32_bf16 v[4:7], v[144:147], v[200:203], v[4:7]
	v_mfma_f32_16x16x32_bf16 v[0:3], v[152:155], v[200:203], v[0:3]
	v_mfma_f32_16x16x32_bf16 v[32:35], v[144:147], v[160:163], v[68:71]
	v_mfma_f32_16x16x32_bf16 v[36:39], v[152:155], v[160:163], v[64:67]
	v_mfma_f32_16x16x32_bf16 v[44:47], v[148:151], v[188:191], v[44:47]
	v_mfma_f32_16x16x32_bf16 v[40:43], v[156:159], v[188:191], v[40:43]
	v_mfma_f32_16x16x32_bf16 v[20:23], v[148:151], v[196:199], v[20:23]
	v_mfma_f32_16x16x32_bf16 v[16:19], v[156:159], v[196:199], v[16:19]
	v_mfma_f32_16x16x32_bf16 v[4:7], v[148:151], v[204:207], v[4:7]
	v_mfma_f32_16x16x32_bf16 v[0:3], v[156:159], v[204:207], v[0:3]
	v_mfma_f32_16x16x32_bf16 v[32:35], v[148:151], v[164:167], v[32:35]
	v_mfma_f32_16x16x32_bf16 v[36:39], v[156:159], v[164:167], v[36:39]
	s_barrier
	s_add_i32 s82, 0, 0x18000
	s_add_i32 s83, 0, 0x1c000
	v_add_u32_e32 v68, s82, v209
	v_add_u32_e32 v156, s83, v209
	ds_read_b128 v[48:51], v68
	ds_read_b128 v[52:55], v68 offset:1024
	ds_read_b128 v[64:67], v68 offset:2048
	ds_read_b128 v[68:71], v68 offset:3072
	ds_read_b128 v[144:147], v156
	ds_read_b128 v[148:151], v156 offset:1024
	ds_read_b128 v[152:155], v156 offset:2048
	ds_read_b128 v[156:159], v156 offset:3072
	s_add_u32 s46, s62, 0x40000
	s_addc_u32 s47, s63, 0
	s_mov_b32 m0, s73
	v_lshl_add_u64 v[216:217], s[46:47], 0, v[174:175]
	ds_read_b128 v[160:163], v211 offset:32768
	ds_read_b128 v[164:167], v211 offset:33792
	ds_read_b128 v[184:187], v211 offset:34816
	ds_read_b128 v[188:191], v211 offset:35840
	ds_read_b128 v[192:195], v211 offset:36864
	ds_read_b128 v[196:199], v211 offset:37888
	ds_read_b128 v[200:203], v211 offset:38912
	ds_read_b128 v[204:207], v211 offset:39936
	global_load_lds_dwordx4 v[216:217], off
	v_lshl_add_u64 v[216:217], s[46:47], 0, v[176:177]
	s_mov_b32 m0, s42
	s_nop 0
	global_load_lds_dwordx4 v[216:217], off
	s_waitcnt vmcnt(8)
	s_waitcnt lgkmcnt(0)
	s_barrier
	s_waitcnt lgkmcnt(0)
	v_mfma_f32_16x16x32_bf16 v[140:143], v[48:51], v[160:163], v[140:143]
	v_mfma_f32_16x16x32_bf16 v[136:139], v[64:67], v[160:163], v[136:139]
	v_mfma_f32_16x16x32_bf16 v[124:127], v[48:51], v[184:187], v[124:127]
	v_mfma_f32_16x16x32_bf16 v[120:123], v[64:67], v[184:187], v[120:123]
	v_mfma_f32_16x16x32_bf16 v[108:111], v[48:51], v[192:195], v[108:111]
	v_mfma_f32_16x16x32_bf16 v[104:107], v[64:67], v[192:195], v[104:107]
	v_mfma_f32_16x16x32_bf16 v[92:95], v[48:51], v[200:203], v[92:95]
	v_mfma_f32_16x16x32_bf16 v[88:91], v[64:67], v[200:203], v[88:91]
	v_mfma_f32_16x16x32_bf16 v[140:143], v[52:55], v[164:167], v[140:143]
	v_mfma_f32_16x16x32_bf16 v[136:139], v[68:71], v[164:167], v[136:139]
	v_mfma_f32_16x16x32_bf16 v[124:127], v[52:55], v[188:191], v[124:127]
	v_mfma_f32_16x16x32_bf16 v[120:123], v[68:71], v[188:191], v[120:123]
	v_mfma_f32_16x16x32_bf16 v[108:111], v[52:55], v[196:199], v[108:111]
	v_mfma_f32_16x16x32_bf16 v[104:107], v[68:71], v[196:199], v[104:107]
	v_mfma_f32_16x16x32_bf16 v[92:95], v[52:55], v[204:207], v[92:95]
	v_mfma_f32_16x16x32_bf16 v[88:91], v[68:71], v[204:207], v[88:91]
	v_mfma_f32_16x16x32_bf16 v[132:135], v[144:147], v[160:163], v[132:135]
	v_mfma_f32_16x16x32_bf16 v[128:131], v[152:155], v[160:163], v[128:131]
	v_mfma_f32_16x16x32_bf16 v[116:119], v[144:147], v[184:187], v[116:119]
	v_mfma_f32_16x16x32_bf16 v[112:115], v[152:155], v[184:187], v[112:115]
	v_mfma_f32_16x16x32_bf16 v[100:103], v[144:147], v[192:195], v[100:103]
	v_mfma_f32_16x16x32_bf16 v[96:99], v[152:155], v[192:195], v[96:99]
	v_mfma_f32_16x16x32_bf16 v[84:87], v[144:147], v[200:203], v[84:87]
	v_mfma_f32_16x16x32_bf16 v[80:83], v[152:155], v[200:203], v[80:83]
	v_mfma_f32_16x16x32_bf16 v[132:135], v[148:151], v[164:167], v[132:135]
	v_mfma_f32_16x16x32_bf16 v[128:131], v[156:159], v[164:167], v[128:131]
	v_mfma_f32_16x16x32_bf16 v[116:119], v[148:151], v[188:191], v[116:119]
	v_mfma_f32_16x16x32_bf16 v[112:115], v[156:159], v[188:191], v[112:115]
	v_mfma_f32_16x16x32_bf16 v[100:103], v[148:151], v[196:199], v[100:103]
	v_mfma_f32_16x16x32_bf16 v[96:99], v[156:159], v[196:199], v[96:99]
	v_mfma_f32_16x16x32_bf16 v[84:87], v[148:151], v[204:207], v[84:87]
	v_mfma_f32_16x16x32_bf16 v[80:83], v[156:159], v[204:207], v[80:83]
	s_barrier
	s_add_i32 s46, s82, s70
	v_lshl_add_u64 v[170:171], v[170:171], 0, s[36:37]
	s_mov_b32 m0, s46
	ds_read_b128 v[160:163], v211 offset:49152
	ds_read_b128 v[164:167], v211 offset:50176
	ds_read_b128 v[184:187], v211 offset:51200
	ds_read_b128 v[188:191], v211 offset:52224
	ds_read_b128 v[192:195], v211 offset:53248
	ds_read_b128 v[196:199], v211 offset:54272
	ds_read_b128 v[200:203], v211 offset:55296
	ds_read_b128 v[204:207], v211 offset:56320
	global_load_lds_dwordx4 v[170:171], off
	s_add_i32 m0, s46, 0x2000
	s_add_u32 s46, s60, 0x40080
	v_lshl_add_u64 v[170:171], v[172:173], 0, s[36:37]
	s_addc_u32 s47, s61, 0
	s_add_i32 s60, s83, s70
	global_load_lds_dwordx4 v[170:171], off
	v_lshl_add_u64 v[170:171], s[46:47], 0, v[168:169]
	s_mov_b32 m0, s60
	s_nop 0
	global_load_lds_dwordx4 v[170:171], off
	v_lshl_add_u64 v[170:171], s[46:47], 0, v[178:179]
	s_add_i32 m0, s60, 0x2000
	s_nop 0
	global_load_lds_dwordx4 v[170:171], off
	v_lshl_add_u64 v[170:171], v[212:213], 0, s[36:37]
	s_mov_b32 m0, s78
	s_nop 0
	global_load_lds_dwordx4 v[170:171], off
	v_lshl_add_u64 v[170:171], v[214:215], 0, s[36:37]
	s_mov_b32 m0, s90
	s_nop 0
	global_load_lds_dwordx4 v[170:171], off
	s_waitcnt vmcnt(8)
	s_waitcnt lgkmcnt(0)
	s_barrier
	s_waitcnt lgkmcnt(0)
	v_mfma_f32_16x16x32_bf16 v[76:79], v[48:51], v[160:163], v[76:79]
	v_mfma_f32_16x16x32_bf16 v[72:75], v[64:67], v[160:163], v[72:75]
	v_mfma_f32_16x16x32_bf16 v[60:63], v[48:51], v[184:187], v[60:63]
	v_mfma_f32_16x16x32_bf16 v[56:59], v[64:67], v[184:187], v[56:59]
	v_mfma_f32_16x16x32_bf16 v[28:31], v[48:51], v[192:195], v[28:31]
	v_mfma_f32_16x16x32_bf16 v[24:27], v[64:67], v[192:195], v[24:27]
	v_mfma_f32_16x16x32_bf16 v[12:15], v[48:51], v[200:203], v[12:15]
	v_mfma_f32_16x16x32_bf16 v[8:11], v[64:67], v[200:203], v[8:11]
	v_mfma_f32_16x16x32_bf16 v[76:79], v[52:55], v[164:167], v[76:79]
	v_mfma_f32_16x16x32_bf16 v[72:75], v[68:71], v[164:167], v[72:75]
	v_mfma_f32_16x16x32_bf16 v[60:63], v[52:55], v[188:191], v[60:63]
	v_mfma_f32_16x16x32_bf16 v[56:59], v[68:71], v[188:191], v[56:59]
	v_mfma_f32_16x16x32_bf16 v[28:31], v[52:55], v[196:199], v[28:31]
	v_mfma_f32_16x16x32_bf16 v[24:27], v[68:71], v[196:199], v[24:27]
	v_mfma_f32_16x16x32_bf16 v[12:15], v[52:55], v[204:207], v[12:15]
	v_mfma_f32_16x16x32_bf16 v[8:11], v[68:71], v[204:207], v[8:11]
	v_mfma_f32_16x16x32_bf16 v[32:35], v[144:147], v[160:163], v[32:35]
	v_mfma_f32_16x16x32_bf16 v[68:71], v[148:151], v[164:167], v[32:35]
	v_mfma_f32_16x16x32_bf16 v[32:35], v[152:155], v[160:163], v[36:39]
	v_mfma_f32_16x16x32_bf16 v[64:67], v[156:159], v[164:167], v[32:35]
	v_mfma_f32_16x16x32_bf16 v[32:35], v[144:147], v[184:187], v[44:47]
	v_mfma_f32_16x16x32_bf16 v[44:47], v[148:151], v[188:191], v[32:35]
	v_mfma_f32_16x16x32_bf16 v[32:35], v[152:155], v[184:187], v[40:43]
	v_mfma_f32_16x16x32_bf16 v[20:23], v[144:147], v[192:195], v[20:23]
	v_mfma_f32_16x16x32_bf16 v[16:19], v[152:155], v[192:195], v[16:19]
	v_mfma_f32_16x16x32_bf16 v[4:7], v[144:147], v[200:203], v[4:7]
	v_mfma_f32_16x16x32_bf16 v[0:3], v[152:155], v[200:203], v[0:3]
	v_mfma_f32_16x16x32_bf16 v[40:43], v[156:159], v[188:191], v[32:35]
	v_mfma_f32_16x16x32_bf16 v[20:23], v[148:151], v[196:199], v[20:23]
	v_mfma_f32_16x16x32_bf16 v[16:19], v[156:159], v[196:199], v[16:19]
	v_mfma_f32_16x16x32_bf16 v[4:7], v[148:151], v[204:207], v[4:7]
	v_mfma_f32_16x16x32_bf16 v[0:3], v[156:159], v[204:207], v[0:3]
	s_barrier
	s_add_i32 s84, s84, 2
	s_add_u32 s77, s77, 0x100
	s_addc_u32 s79, s79, 0
	s_add_u32 s58, s58, 0x100
	s_addc_u32 s59, s59, 0
	s_cmp_gt_u32 s84, 13
	s_cbranch_scc0 .LBB0_654
	s_and_b64 vcc, exec, s[22:23]
	s_cbranch_vccz .LBB0_657
	s_barrier

.LBB0_732:
	s_add_u32 s47, s66, 0xfffc0080
	s_addc_u32 s68, s67, -1
	s_add_i32 s82, 0, 0x10000
	s_cmp_eq_u32 s46, 12
	s_cselect_b32 s71, s59, s68
	s_cselect_b32 s70, vcc_lo, s47
	s_cselect_b32 s69, s57, s84
	s_cselect_b32 s68, vcc_hi, s96
	s_add_i32 s47, 0, 0x14000
	v_add_u32_e32 v140, s82, v162
	v_add_u32_e32 v157, s47, v162
	ds_read_b128 v[128:131], v140
	ds_read_b128 v[132:135], v140 offset:1024
	ds_read_b128 v[136:139], v140 offset:2048
	ds_read_b128 v[140:143], v140 offset:3072
	ds_read_b128 v[176:179], v157
	ds_read_b128 v[180:183], v157 offset:1024
	ds_read_b128 v[184:187], v157 offset:2048
	ds_read_b128 v[188:191], v157 offset:3072
	v_lshl_add_u64 v[170:171], s[66:67], 0, v[152:153]
	s_add_i32 m0, s65, 0xc000
	ds_read_b128 v[192:195], v164
	ds_read_b128 v[196:199], v164 offset:1024
	ds_read_b128 v[200:203], v164 offset:2048
	ds_read_b128 v[204:207], v164 offset:3072
	ds_read_b128 v[208:211], v164 offset:4096
	ds_read_b128 v[212:215], v164 offset:5120
	ds_read_b128 v[216:219], v164 offset:6144
	ds_read_b128 v[220:223], v164 offset:7168
	global_load_lds_dwordx4 v[170:171], off
	v_lshl_add_u64 v[170:171], s[66:67], 0, v[150:151]
	s_add_i32 m0, s65, 0xe000
	s_nop 0
	global_load_lds_dwordx4 v[170:171], off
	s_waitcnt vmcnt(8)
	s_waitcnt lgkmcnt(0)
	s_barrier
	s_waitcnt lgkmcnt(0)
	v_mfma_f32_16x16x32_bf16 v[124:127], v[128:131], v[192:195], v[124:127]
	v_mfma_f32_16x16x32_bf16 v[120:123], v[136:139], v[192:195], v[120:123]
	v_mfma_f32_16x16x32_bf16 v[116:119], v[128:131], v[200:203], v[116:119]
	v_mfma_f32_16x16x32_bf16 v[112:115], v[136:139], v[200:203], v[112:115]
	v_mfma_f32_16x16x32_bf16 v[92:95], v[128:131], v[208:211], v[92:95]
	v_mfma_f32_16x16x32_bf16 v[88:91], v[136:139], v[208:211], v[88:91]
	v_mfma_f32_16x16x32_bf16 v[76:79], v[128:131], v[216:219], v[76:79]
	v_mfma_f32_16x16x32_bf16 v[72:75], v[136:139], v[216:219], v[72:75]
	v_mfma_f32_16x16x32_bf16 v[124:127], v[132:135], v[196:199], v[124:127]
	v_mfma_f32_16x16x32_bf16 v[120:123], v[140:143], v[196:199], v[120:123]
	v_mfma_f32_16x16x32_bf16 v[116:119], v[132:135], v[204:207], v[116:119]
	v_mfma_f32_16x16x32_bf16 v[112:115], v[140:143], v[204:207], v[112:115]
	v_mfma_f32_16x16x32_bf16 v[92:95], v[132:135], v[212:215], v[92:95]
	v_mfma_f32_16x16x32_bf16 v[88:91], v[140:143], v[212:215], v[88:91]
	v_mfma_f32_16x16x32_bf16 v[76:79], v[132:135], v[220:223], v[76:79]
	v_mfma_f32_16x16x32_bf16 v[72:75], v[140:143], v[220:223], v[72:75]
	v_mfma_f32_16x16x32_bf16 v[108:111], v[176:179], v[192:195], v[108:111]
	v_mfma_f32_16x16x32_bf16 v[104:107], v[184:187], v[192:195], v[104:107]
	v_mfma_f32_16x16x32_bf16 v[100:103], v[176:179], v[200:203], v[100:103]
	v_mfma_f32_16x16x32_bf16 v[96:99], v[184:187], v[200:203], v[96:99]
	v_mfma_f32_16x16x32_bf16 v[84:87], v[176:179], v[208:211], v[84:87]
	v_mfma_f32_16x16x32_bf16 v[80:83], v[184:187], v[208:211], v[80:83]
	v_mfma_f32_16x16x32_bf16 v[68:71], v[176:179], v[216:219], v[68:71]
	v_mfma_f32_16x16x32_bf16 v[64:67], v[184:187], v[216:219], v[64:67]
	v_mfma_f32_16x16x32_bf16 v[108:111], v[180:183], v[196:199], v[108:111]
	v_mfma_f32_16x16x32_bf16 v[104:107], v[188:191], v[196:199], v[104:107]
	v_mfma_f32_16x16x32_bf16 v[100:103], v[180:183], v[204:207], v[100:103]
	v_mfma_f32_16x16x32_bf16 v[96:99], v[188:191], v[204:207], v[96:99]
	v_mfma_f32_16x16x32_bf16 v[84:87], v[180:183], v[212:215], v[84:87]
	v_mfma_f32_16x16x32_bf16 v[80:83], v[188:191], v[212:215], v[80:83]
	v_mfma_f32_16x16x32_bf16 v[68:71], v[180:183], v[220:223], v[68:71]
	v_mfma_f32_16x16x32_bf16 v[64:67], v[188:191], v[220:223], v[64:67]
	s_barrier
	s_add_i32 s82, s82, s90
	v_lshl_add_u64 v[170:171], s[68:69], 0, v[168:169]
	s_mov_b32 m0, s82
	ds_read_b128 v[192:195], v164 offset:16384
	ds_read_b128 v[196:199], v164 offset:17408
	ds_read_b128 v[200:203], v164 offset:18432
	ds_read_b128 v[204:207], v164 offset:19456
	ds_read_b128 v[208:211], v164 offset:20480
	ds_read_b128 v[212:215], v164 offset:21504
	ds_read_b128 v[216:219], v164 offset:22528
	ds_read_b128 v[220:223], v164 offset:23552
	global_load_lds_dwordx4 v[170:171], off
	s_add_i32 m0, s82, 0x2000
	s_add_u32 s82, s68, 0x40000
	v_lshl_add_u64 v[172:173], s[68:69], 0, v[144:145]
	s_addc_u32 s83, s69, 0
	s_add_i32 s47, s47, s90
	global_load_lds_dwordx4 v[172:173], off
	v_lshl_add_u64 v[224:225], s[82:83], 0, v[168:169]
	s_mov_b32 m0, s47
	v_lshl_add_u64 v[228:229], s[70:71], 0, v[146:147]
	global_load_lds_dwordx4 v[224:225], off
	v_lshl_add_u64 v[224:225], s[82:83], 0, v[144:145]
	s_add_i32 m0, s47, 0x2000
	s_nop 0
	global_load_lds_dwordx4 v[224:225], off
	v_lshl_add_u64 v[224:225], s[70:71], 0, v[148:149]
	s_mov_b32 m0, s65
	s_nop 0
	global_load_lds_dwordx4 v[224:225], off
	s_mov_b32 m0, s92
	s_nop 0
	global_load_lds_dwordx4 v[228:229], off
	s_waitcnt vmcnt(8)
	s_waitcnt lgkmcnt(0)
	s_barrier
	s_waitcnt lgkmcnt(0)
	v_mfma_f32_16x16x32_bf16 v[60:63], v[128:131], v[192:195], v[60:63]
	v_mfma_f32_16x16x32_bf16 v[56:59], v[136:139], v[192:195], v[56:59]
	v_mfma_f32_16x16x32_bf16 v[44:47], v[128:131], v[200:203], v[44:47]
	v_mfma_f32_16x16x32_bf16 v[40:43], v[136:139], v[200:203], v[40:43]
	v_mfma_f32_16x16x32_bf16 v[28:31], v[128:131], v[208:211], v[28:31]
	v_mfma_f32_16x16x32_bf16 v[24:27], v[136:139], v[208:211], v[24:27]
	v_mfma_f32_16x16x32_bf16 v[12:15], v[128:131], v[216:219], v[12:15]
	v_mfma_f32_16x16x32_bf16 v[8:11], v[136:139], v[216:219], v[8:11]
	v_mfma_f32_16x16x32_bf16 v[60:63], v[132:135], v[196:199], v[60:63]
	v_mfma_f32_16x16x32_bf16 v[56:59], v[140:143], v[196:199], v[56:59]
	v_mfma_f32_16x16x32_bf16 v[44:47], v[132:135], v[204:207], v[44:47]
	v_mfma_f32_16x16x32_bf16 v[40:43], v[140:143], v[204:207], v[40:43]
	v_mfma_f32_16x16x32_bf16 v[28:31], v[132:135], v[212:215], v[28:31]
	v_mfma_f32_16x16x32_bf16 v[24:27], v[140:143], v[212:215], v[24:27]
	v_mfma_f32_16x16x32_bf16 v[12:15], v[132:135], v[220:223], v[12:15]
	v_mfma_f32_16x16x32_bf16 v[8:11], v[140:143], v[220:223], v[8:11]
	v_mfma_f32_16x16x32_bf16 v[52:55], v[176:179], v[192:195], v[52:55]
	v_mfma_f32_16x16x32_bf16 v[48:51], v[184:187], v[192:195], v[48:51]
	v_mfma_f32_16x16x32_bf16 v[36:39], v[176:179], v[200:203], v[36:39]
	v_mfma_f32_16x16x32_bf16 v[32:35], v[184:187], v[200:203], v[32:35]
	v_mfma_f32_16x16x32_bf16 v[20:23], v[176:179], v[208:211], v[20:23]
	v_mfma_f32_16x16x32_bf16 v[16:19], v[184:187], v[208:211], v[16:19]
	v_mfma_f32_16x16x32_bf16 v[4:7], v[176:179], v[216:219], v[4:7]
	v_mfma_f32_16x16x32_bf16 v[0:3], v[184:187], v[216:219], v[0:3]
	v_mfma_f32_16x16x32_bf16 v[52:55], v[180:183], v[196:199], v[52:55]
	v_mfma_f32_16x16x32_bf16 v[48:51], v[188:191], v[196:199], v[48:51]
	v_mfma_f32_16x16x32_bf16 v[36:39], v[180:183], v[204:207], v[36:39]
	v_mfma_f32_16x16x32_bf16 v[32:35], v[188:191], v[204:207], v[32:35]
	v_mfma_f32_16x16x32_bf16 v[20:23], v[180:183], v[212:215], v[20:23]
	v_mfma_f32_16x16x32_bf16 v[16:19], v[188:191], v[212:215], v[16:19]
	v_mfma_f32_16x16x32_bf16 v[4:7], v[180:183], v[220:223], v[4:7]
	v_mfma_f32_16x16x32_bf16 v[0:3], v[188:191], v[220:223], v[0:3]
	s_barrier
	s_add_i32 s47, 0, 0x18000
	s_add_i32 s82, 0, 0x1c000
	v_add_u32_e32 v140, s47, v162
	v_add_u32_e32 v157, s82, v162
	ds_read_b128 v[128:131], v140
	ds_read_b128 v[132:135], v140 offset:1024
	ds_read_b128 v[136:139], v140 offset:2048
	ds_read_b128 v[140:143], v140 offset:3072
	ds_read_b128 v[176:179], v157
	ds_read_b128 v[180:183], v157 offset:1024
	ds_read_b128 v[184:187], v157 offset:2048
	ds_read_b128 v[188:191], v157 offset:3072
	s_add_u32 s70, s70, 0x40000
	s_addc_u32 s71, s71, 0
	s_mov_b32 m0, s93
	v_lshl_add_u64 v[230:231], s[70:71], 0, v[148:149]
	ds_read_b128 v[192:195], v164 offset:32768
	ds_read_b128 v[196:199], v164 offset:33792
	ds_read_b128 v[200:203], v164 offset:34816
	ds_read_b128 v[204:207], v164 offset:35840
	ds_read_b128 v[208:211], v164 offset:36864
	ds_read_b128 v[212:215], v164 offset:37888
	ds_read_b128 v[216:219], v164 offset:38912
	ds_read_b128 v[220:223], v164 offset:39936
	global_load_lds_dwordx4 v[230:231], off
	v_lshl_add_u64 v[230:231], s[70:71], 0, v[146:147]
	s_mov_b32 m0, s94
	s_nop 0
	global_load_lds_dwordx4 v[230:231], off
	s_waitcnt vmcnt(8)
	s_waitcnt lgkmcnt(0)
	s_barrier
	s_waitcnt lgkmcnt(0)
	v_mfma_f32_16x16x32_bf16 v[124:127], v[128:131], v[192:195], v[124:127]
	v_mfma_f32_16x16x32_bf16 v[120:123], v[136:139], v[192:195], v[120:123]
	v_mfma_f32_16x16x32_bf16 v[116:119], v[128:131], v[200:203], v[116:119]
	v_mfma_f32_16x16x32_bf16 v[112:115], v[136:139], v[200:203], v[112:115]
	v_mfma_f32_16x16x32_bf16 v[92:95], v[128:131], v[208:211], v[92:95]
	v_mfma_f32_16x16x32_bf16 v[88:91], v[136:139], v[208:211], v[88:91]
	v_mfma_f32_16x16x32_bf16 v[76:79], v[128:131], v[216:219], v[76:79]
	v_mfma_f32_16x16x32_bf16 v[72:75], v[136:139], v[216:219], v[72:75]
	v_mfma_f32_16x16x32_bf16 v[124:127], v[132:135], v[196:199], v[124:127]
	v_mfma_f32_16x16x32_bf16 v[120:123], v[140:143], v[196:199], v[120:123]
	v_mfma_f32_16x16x32_bf16 v[116:119], v[132:135], v[204:207], v[116:119]
	v_mfma_f32_16x16x32_bf16 v[112:115], v[140:143], v[204:207], v[112:115]
	v_mfma_f32_16x16x32_bf16 v[92:95], v[132:135], v[212:215], v[92:95]
	v_mfma_f32_16x16x32_bf16 v[88:91], v[140:143], v[212:215], v[88:91]
	v_mfma_f32_16x16x32_bf16 v[76:79], v[132:135], v[220:223], v[76:79]
	v_mfma_f32_16x16x32_bf16 v[72:75], v[140:143], v[220:223], v[72:75]
	v_mfma_f32_16x16x32_bf16 v[108:111], v[176:179], v[192:195], v[108:111]
	v_mfma_f32_16x16x32_bf16 v[104:107], v[184:187], v[192:195], v[104:107]
	v_mfma_f32_16x16x32_bf16 v[100:103], v[176:179], v[200:203], v[100:103]
	v_mfma_f32_16x16x32_bf16 v[96:99], v[184:187], v[200:203], v[96:99]
	v_mfma_f32_16x16x32_bf16 v[84:87], v[176:179], v[208:211], v[84:87]
	v_mfma_f32_16x16x32_bf16 v[80:83], v[184:187], v[208:211], v[80:83]
	v_mfma_f32_16x16x32_bf16 v[68:71], v[176:179], v[216:219], v[68:71]
	v_mfma_f32_16x16x32_bf16 v[64:67], v[184:187], v[216:219], v[64:67]
	v_mfma_f32_16x16x32_bf16 v[108:111], v[180:183], v[196:199], v[108:111]
	v_mfma_f32_16x16x32_bf16 v[104:107], v[188:191], v[196:199], v[104:107]
	v_mfma_f32_16x16x32_bf16 v[100:103], v[180:183], v[204:207], v[100:103]
	v_mfma_f32_16x16x32_bf16 v[96:99], v[188:191], v[204:207], v[96:99]
	v_mfma_f32_16x16x32_bf16 v[84:87], v[180:183], v[212:215], v[84:87]
	v_mfma_f32_16x16x32_bf16 v[80:83], v[188:191], v[212:215], v[80:83]
	v_mfma_f32_16x16x32_bf16 v[68:71], v[180:183], v[220:223], v[68:71]
	v_mfma_f32_16x16x32_bf16 v[64:67], v[188:191], v[220:223], v[64:67]
	s_barrier
	s_add_i32 s47, s47, s90
	v_lshl_add_u64 v[170:171], v[170:171], 0, s[36:37]
	s_mov_b32 m0, s47
	ds_read_b128 v[192:195], v164 offset:49152
	ds_read_b128 v[196:199], v164 offset:50176
	ds_read_b128 v[200:203], v164 offset:51200
	ds_read_b128 v[204:207], v164 offset:52224
	ds_read_b128 v[208:211], v164 offset:53248
	ds_read_b128 v[212:215], v164 offset:54272
	ds_read_b128 v[216:219], v164 offset:55296
	ds_read_b128 v[220:223], v164 offset:56320
	global_load_lds_dwordx4 v[170:171], off
	s_add_i32 m0, s47, 0x2000
	s_add_u32 s68, s68, 0x40080
	v_lshl_add_u64 v[170:171], v[172:173], 0, s[36:37]
	s_addc_u32 s69, s69, 0
	s_add_i32 s47, s82, s90
	global_load_lds_dwordx4 v[170:171], off
	v_lshl_add_u64 v[170:171], s[68:69], 0, v[168:169]
	s_mov_b32 m0, s47
	s_nop 0
	global_load_lds_dwordx4 v[170:171], off
	v_lshl_add_u64 v[170:171], s[68:69], 0, v[144:145]
	s_add_i32 m0, s47, 0x2000
	s_nop 0
	global_load_lds_dwordx4 v[170:171], off
	v_lshl_add_u64 v[170:171], v[224:225], 0, s[36:37]
	s_mov_b32 m0, s79
	s_nop 0
	global_load_lds_dwordx4 v[170:171], off
	v_lshl_add_u64 v[170:171], v[228:229], 0, s[36:37]
	s_mov_b32 m0, s30
	s_nop 0
	global_load_lds_dwordx4 v[170:171], off
	s_waitcnt vmcnt(8)
	s_waitcnt lgkmcnt(0)
	s_barrier
	s_waitcnt lgkmcnt(0)
	v_mfma_f32_16x16x32_bf16 v[60:63], v[128:131], v[192:195], v[60:63]
	v_mfma_f32_16x16x32_bf16 v[56:59], v[136:139], v[192:195], v[56:59]
	v_mfma_f32_16x16x32_bf16 v[44:47], v[128:131], v[200:203], v[44:47]
	v_mfma_f32_16x16x32_bf16 v[40:43], v[136:139], v[200:203], v[40:43]
	v_mfma_f32_16x16x32_bf16 v[28:31], v[128:131], v[208:211], v[28:31]
	v_mfma_f32_16x16x32_bf16 v[24:27], v[136:139], v[208:211], v[24:27]
	v_mfma_f32_16x16x32_bf16 v[12:15], v[128:131], v[216:219], v[12:15]
	v_mfma_f32_16x16x32_bf16 v[8:11], v[136:139], v[216:219], v[8:11]
	v_mfma_f32_16x16x32_bf16 v[60:63], v[132:135], v[196:199], v[60:63]
	v_mfma_f32_16x16x32_bf16 v[56:59], v[140:143], v[196:199], v[56:59]
	v_mfma_f32_16x16x32_bf16 v[44:47], v[132:135], v[204:207], v[44:47]
	v_mfma_f32_16x16x32_bf16 v[40:43], v[140:143], v[204:207], v[40:43]
	v_mfma_f32_16x16x32_bf16 v[28:31], v[132:135], v[212:215], v[28:31]
	v_mfma_f32_16x16x32_bf16 v[24:27], v[140:143], v[212:215], v[24:27]
	v_mfma_f32_16x16x32_bf16 v[12:15], v[132:135], v[220:223], v[12:15]
	v_mfma_f32_16x16x32_bf16 v[8:11], v[140:143], v[220:223], v[8:11]
	v_mfma_f32_16x16x32_bf16 v[52:55], v[176:179], v[192:195], v[52:55]
	v_mfma_f32_16x16x32_bf16 v[48:51], v[184:187], v[192:195], v[48:51]
	v_mfma_f32_16x16x32_bf16 v[36:39], v[176:179], v[200:203], v[36:39]
	v_mfma_f32_16x16x32_bf16 v[32:35], v[184:187], v[200:203], v[32:35]
	v_mfma_f32_16x16x32_bf16 v[20:23], v[176:179], v[208:211], v[20:23]
	v_mfma_f32_16x16x32_bf16 v[16:19], v[184:187], v[208:211], v[16:19]
	v_mfma_f32_16x16x32_bf16 v[4:7], v[176:179], v[216:219], v[4:7]
	v_mfma_f32_16x16x32_bf16 v[0:3], v[184:187], v[216:219], v[0:3]
	v_mfma_f32_16x16x32_bf16 v[52:55], v[180:183], v[196:199], v[52:55]
	v_mfma_f32_16x16x32_bf16 v[48:51], v[188:191], v[196:199], v[48:51]
	v_mfma_f32_16x16x32_bf16 v[36:39], v[180:183], v[204:207], v[36:39]
	v_mfma_f32_16x16x32_bf16 v[32:35], v[188:191], v[204:207], v[32:35]
	v_mfma_f32_16x16x32_bf16 v[20:23], v[180:183], v[212:215], v[20:23]
	v_mfma_f32_16x16x32_bf16 v[16:19], v[188:191], v[212:215], v[16:19]
	v_mfma_f32_16x16x32_bf16 v[4:7], v[180:183], v[220:223], v[4:7]
	v_mfma_f32_16x16x32_bf16 v[0:3], v[188:191], v[220:223], v[0:3]
	s_barrier
	s_add_i32 s46, s46, 2
	s_add_u32 s96, s96, 0x100
	s_addc_u32 s84, s84, 0
	s_add_u32 s66, s66, 0x100
	s_addc_u32 s67, s67, 0
	s_cmp_gt_u32 s46, 13
	s_cbranch_scc0 .LBB0_732
	s_and_b64 vcc, exec, s[54:55]
	s_cbranch_vccz .LBB0_735
	s_barrier

.LBB0_843:
	s_add_u32 s6, s50, 0x100
	s_addc_u32 s7, s51, 0
	s_add_i32 s72, 0, 0x10000
	s_cmp_eq_u32 s71, 40
	s_cselect_b32 s55, s47, s7
	s_cselect_b32 s54, s46, s6
	s_cselect_b32 s53, s49, s70
	s_cselect_b32 s52, s48, s69
	s_add_i32 s73, 0, 0x14000
	v_add_u32_e32 v84, s72, v216
	v_add_u32_e32 v156, s73, v216
	ds_read_b128 v[68:71], v84
	ds_read_b128 v[76:79], v84 offset:1024
	ds_read_b128 v[80:83], v84 offset:2048
	ds_read_b128 v[84:87], v84 offset:3072
	ds_read_b128 v[144:147], v156
	ds_read_b128 v[148:151], v156 offset:1024
	ds_read_b128 v[152:155], v156 offset:2048
	ds_read_b128 v[156:159], v156 offset:3072
	v_lshl_add_u64 v[170:171], s[50:51], 0, v[182:183]
	s_add_i32 m0, s56, 0xc000
	ds_read_b128 v[160:163], v218
	ds_read_b128 v[164:167], v218 offset:1024
	ds_read_b128 v[184:187], v218 offset:2048
	ds_read_b128 v[188:191], v218 offset:3072
	ds_read_b128 v[192:195], v218 offset:4096
	ds_read_b128 v[196:199], v218 offset:5120
	ds_read_b128 v[200:203], v218 offset:6144
	ds_read_b128 v[204:207], v218 offset:7168
	global_load_lds_dwordx4 v[170:171], off
	v_lshl_add_u64 v[170:171], s[50:51], 0, v[180:181]
	s_add_i32 m0, s56, 0xe000
	s_nop 0
	global_load_lds_dwordx4 v[170:171], off
	s_waitcnt vmcnt(8)
	s_waitcnt lgkmcnt(0)
	s_barrier
	s_waitcnt lgkmcnt(0)
	v_mfma_f32_16x16x32_bf16 v[140:143], v[68:71], v[160:163], v[140:143]
	v_mfma_f32_16x16x32_bf16 v[136:139], v[80:83], v[160:163], v[136:139]
	v_mfma_f32_16x16x32_bf16 v[124:127], v[68:71], v[184:187], v[124:127]
	v_mfma_f32_16x16x32_bf16 v[120:123], v[80:83], v[184:187], v[120:123]
	v_mfma_f32_16x16x32_bf16 v[108:111], v[68:71], v[192:195], v[108:111]
	v_mfma_f32_16x16x32_bf16 v[104:107], v[80:83], v[192:195], v[104:107]
	v_mfma_f32_16x16x32_bf16 v[92:95], v[68:71], v[200:203], v[92:95]
	v_mfma_f32_16x16x32_bf16 v[88:91], v[80:83], v[200:203], v[88:91]
	v_mfma_f32_16x16x32_bf16 v[140:143], v[76:79], v[164:167], v[140:143]
	v_mfma_f32_16x16x32_bf16 v[136:139], v[84:87], v[164:167], v[136:139]
	v_mfma_f32_16x16x32_bf16 v[124:127], v[76:79], v[188:191], v[124:127]
	v_mfma_f32_16x16x32_bf16 v[120:123], v[84:87], v[188:191], v[120:123]
	v_mfma_f32_16x16x32_bf16 v[108:111], v[76:79], v[196:199], v[108:111]
	v_mfma_f32_16x16x32_bf16 v[104:107], v[84:87], v[196:199], v[104:107]
	v_mfma_f32_16x16x32_bf16 v[92:95], v[76:79], v[204:207], v[92:95]
	v_mfma_f32_16x16x32_bf16 v[88:91], v[84:87], v[204:207], v[88:91]
	v_mfma_f32_16x16x32_bf16 v[132:135], v[144:147], v[160:163], v[132:135]
	v_mfma_f32_16x16x32_bf16 v[128:131], v[152:155], v[160:163], v[128:131]
	v_mfma_f32_16x16x32_bf16 v[116:119], v[144:147], v[184:187], v[116:119]
	v_mfma_f32_16x16x32_bf16 v[112:115], v[152:155], v[184:187], v[112:115]
	v_mfma_f32_16x16x32_bf16 v[100:103], v[144:147], v[192:195], v[100:103]
	v_mfma_f32_16x16x32_bf16 v[96:99], v[152:155], v[192:195], v[96:99]
	v_mfma_f32_16x16x32_bf16 v[72:75], v[144:147], v[200:203], v[72:75]
	v_mfma_f32_16x16x32_bf16 v[64:67], v[152:155], v[200:203], v[64:67]
	v_mfma_f32_16x16x32_bf16 v[132:135], v[148:151], v[164:167], v[132:135]
	v_mfma_f32_16x16x32_bf16 v[128:131], v[156:159], v[164:167], v[128:131]
	v_mfma_f32_16x16x32_bf16 v[116:119], v[148:151], v[188:191], v[116:119]
	v_mfma_f32_16x16x32_bf16 v[112:115], v[156:159], v[188:191], v[112:115]
	v_mfma_f32_16x16x32_bf16 v[100:103], v[148:151], v[196:199], v[100:103]
	v_mfma_f32_16x16x32_bf16 v[96:99], v[156:159], v[196:199], v[96:99]
	v_mfma_f32_16x16x32_bf16 v[72:75], v[148:151], v[204:207], v[72:75]
	v_mfma_f32_16x16x32_bf16 v[64:67], v[156:159], v[204:207], v[64:67]
	s_barrier
	s_add_i32 s50, s72, s43
	v_lshl_add_u64 v[170:171], s[52:53], 0, v[168:169]
	s_mov_b32 m0, s50
	ds_read_b128 v[160:163], v218 offset:16384
	ds_read_b128 v[164:167], v218 offset:17408
	ds_read_b128 v[184:187], v218 offset:18432
	ds_read_b128 v[188:191], v218 offset:19456
	ds_read_b128 v[192:195], v218 offset:20480
	ds_read_b128 v[196:199], v218 offset:21504
	ds_read_b128 v[200:203], v218 offset:22528
	ds_read_b128 v[204:207], v218 offset:23552
	global_load_lds_dwordx4 v[170:171], off
	s_add_i32 m0, s50, 0x2000
	s_add_u32 s50, s52, 0xb0000
	v_lshl_add_u64 v[172:173], s[52:53], 0, v[178:179]
	s_addc_u32 s51, s53, 0
	s_add_i32 s72, s73, s43
	global_load_lds_dwordx4 v[172:173], off
	v_lshl_add_u64 v[208:209], s[50:51], 0, v[168:169]
	s_mov_b32 m0, s72
	v_lshl_add_u64 v[210:211], s[54:55], 0, v[176:177]
	global_load_lds_dwordx4 v[208:209], off
	v_lshl_add_u64 v[208:209], s[50:51], 0, v[178:179]
	s_add_i32 m0, s72, 0x2000
	s_nop 0
	global_load_lds_dwordx4 v[208:209], off
	v_lshl_add_u64 v[208:209], s[54:55], 0, v[174:175]
	s_mov_b32 m0, s56
	s_nop 0
	global_load_lds_dwordx4 v[208:209], off
	s_mov_b32 m0, s57
	s_nop 0
	global_load_lds_dwordx4 v[210:211], off
	s_waitcnt vmcnt(8)
	s_waitcnt lgkmcnt(0)
	s_barrier
	s_waitcnt lgkmcnt(0)
	v_mfma_f32_16x16x32_bf16 v[60:63], v[68:71], v[160:163], v[60:63]
	v_mfma_f32_16x16x32_bf16 v[56:59], v[80:83], v[160:163], v[56:59]
	v_mfma_f32_16x16x32_bf16 v[44:47], v[68:71], v[184:187], v[44:47]
	v_mfma_f32_16x16x32_bf16 v[40:43], v[80:83], v[184:187], v[40:43]
	v_mfma_f32_16x16x32_bf16 v[28:31], v[68:71], v[192:195], v[28:31]
	v_mfma_f32_16x16x32_bf16 v[24:27], v[80:83], v[192:195], v[24:27]
	v_mfma_f32_16x16x32_bf16 v[12:15], v[68:71], v[200:203], v[12:15]
	v_mfma_f32_16x16x32_bf16 v[8:11], v[80:83], v[200:203], v[8:11]
	v_mfma_f32_16x16x32_bf16 v[60:63], v[76:79], v[164:167], v[60:63]
	v_mfma_f32_16x16x32_bf16 v[56:59], v[84:87], v[164:167], v[56:59]
	v_mfma_f32_16x16x32_bf16 v[44:47], v[76:79], v[188:191], v[44:47]
	v_mfma_f32_16x16x32_bf16 v[40:43], v[84:87], v[188:191], v[40:43]
	v_mfma_f32_16x16x32_bf16 v[28:31], v[76:79], v[196:199], v[28:31]
	v_mfma_f32_16x16x32_bf16 v[24:27], v[84:87], v[196:199], v[24:27]
	v_mfma_f32_16x16x32_bf16 v[12:15], v[76:79], v[204:207], v[12:15]
	v_mfma_f32_16x16x32_bf16 v[8:11], v[84:87], v[204:207], v[8:11]
	v_mfma_f32_16x16x32_bf16 v[52:55], v[144:147], v[160:163], v[52:55]
	v_mfma_f32_16x16x32_bf16 v[48:51], v[152:155], v[160:163], v[48:51]
	v_mfma_f32_16x16x32_bf16 v[36:39], v[144:147], v[184:187], v[36:39]
	v_mfma_f32_16x16x32_bf16 v[32:35], v[152:155], v[184:187], v[32:35]
	v_mfma_f32_16x16x32_bf16 v[20:23], v[144:147], v[192:195], v[20:23]
	v_mfma_f32_16x16x32_bf16 v[16:19], v[152:155], v[192:195], v[16:19]
	v_mfma_f32_16x16x32_bf16 v[4:7], v[144:147], v[200:203], v[4:7]
	v_mfma_f32_16x16x32_bf16 v[0:3], v[152:155], v[200:203], v[0:3]
	v_mfma_f32_16x16x32_bf16 v[52:55], v[148:151], v[164:167], v[52:55]
	v_mfma_f32_16x16x32_bf16 v[48:51], v[156:159], v[164:167], v[48:51]
	v_mfma_f32_16x16x32_bf16 v[36:39], v[148:151], v[188:191], v[36:39]
	v_mfma_f32_16x16x32_bf16 v[32:35], v[156:159], v[188:191], v[32:35]
	v_mfma_f32_16x16x32_bf16 v[20:23], v[148:151], v[196:199], v[20:23]
	v_mfma_f32_16x16x32_bf16 v[16:19], v[156:159], v[196:199], v[16:19]
	v_mfma_f32_16x16x32_bf16 v[4:7], v[148:151], v[204:207], v[4:7]
	v_mfma_f32_16x16x32_bf16 v[0:3], v[156:159], v[204:207], v[0:3]
	s_barrier
	s_add_i32 s72, 0, 0x18000
	s_add_i32 s73, 0, 0x1c000
	v_add_u32_e32 v84, s72, v216
	v_add_u32_e32 v156, s73, v216
	ds_read_b128 v[68:71], v84
	ds_read_b128 v[76:79], v84 offset:1024
	ds_read_b128 v[80:83], v84 offset:2048
	ds_read_b128 v[84:87], v84 offset:3072
	ds_read_b128 v[144:147], v156
	ds_read_b128 v[148:151], v156 offset:1024
	ds_read_b128 v[152:155], v156 offset:2048
	ds_read_b128 v[156:159], v156 offset:3072
	s_add_u32 s50, s54, 0xb0000
	s_addc_u32 s51, s55, 0
	s_mov_b32 m0, s58
	v_lshl_add_u64 v[212:213], s[50:51], 0, v[174:175]
	ds_read_b128 v[160:163], v218 offset:32768
	ds_read_b128 v[164:167], v218 offset:33792
	ds_read_b128 v[184:187], v218 offset:34816
	ds_read_b128 v[188:191], v218 offset:35840
	ds_read_b128 v[192:195], v218 offset:36864
	ds_read_b128 v[196:199], v218 offset:37888
	ds_read_b128 v[200:203], v218 offset:38912
	ds_read_b128 v[204:207], v218 offset:39936
	global_load_lds_dwordx4 v[212:213], off
	v_lshl_add_u64 v[212:213], s[50:51], 0, v[176:177]
	s_mov_b32 m0, s59
	s_nop 0
	global_load_lds_dwordx4 v[212:213], off
	s_waitcnt vmcnt(8)
	s_waitcnt lgkmcnt(0)
	s_barrier
	s_waitcnt lgkmcnt(0)
	v_mfma_f32_16x16x32_bf16 v[140:143], v[68:71], v[160:163], v[140:143]
	v_mfma_f32_16x16x32_bf16 v[136:139], v[80:83], v[160:163], v[136:139]
	v_mfma_f32_16x16x32_bf16 v[124:127], v[68:71], v[184:187], v[124:127]
	v_mfma_f32_16x16x32_bf16 v[120:123], v[80:83], v[184:187], v[120:123]
	v_mfma_f32_16x16x32_bf16 v[108:111], v[68:71], v[192:195], v[108:111]
	v_mfma_f32_16x16x32_bf16 v[104:107], v[80:83], v[192:195], v[104:107]
	v_mfma_f32_16x16x32_bf16 v[92:95], v[68:71], v[200:203], v[92:95]
	v_mfma_f32_16x16x32_bf16 v[88:91], v[80:83], v[200:203], v[88:91]
	v_mfma_f32_16x16x32_bf16 v[140:143], v[76:79], v[164:167], v[140:143]
	v_mfma_f32_16x16x32_bf16 v[136:139], v[84:87], v[164:167], v[136:139]
	v_mfma_f32_16x16x32_bf16 v[124:127], v[76:79], v[188:191], v[124:127]
	v_mfma_f32_16x16x32_bf16 v[120:123], v[84:87], v[188:191], v[120:123]
	v_mfma_f32_16x16x32_bf16 v[108:111], v[76:79], v[196:199], v[108:111]
	v_mfma_f32_16x16x32_bf16 v[104:107], v[84:87], v[196:199], v[104:107]
	v_mfma_f32_16x16x32_bf16 v[92:95], v[76:79], v[204:207], v[92:95]
	v_mfma_f32_16x16x32_bf16 v[88:91], v[84:87], v[204:207], v[88:91]
	v_mfma_f32_16x16x32_bf16 v[132:135], v[144:147], v[160:163], v[132:135]
	v_mfma_f32_16x16x32_bf16 v[128:131], v[152:155], v[160:163], v[128:131]
	v_mfma_f32_16x16x32_bf16 v[116:119], v[144:147], v[184:187], v[116:119]
	v_mfma_f32_16x16x32_bf16 v[112:115], v[152:155], v[184:187], v[112:115]
	v_mfma_f32_16x16x32_bf16 v[100:103], v[144:147], v[192:195], v[100:103]
	v_mfma_f32_16x16x32_bf16 v[96:99], v[152:155], v[192:195], v[96:99]
	v_mfma_f32_16x16x32_bf16 v[72:75], v[144:147], v[200:203], v[72:75]
	v_mfma_f32_16x16x32_bf16 v[64:67], v[152:155], v[200:203], v[64:67]
	v_mfma_f32_16x16x32_bf16 v[132:135], v[148:151], v[164:167], v[132:135]
	v_mfma_f32_16x16x32_bf16 v[128:131], v[156:159], v[164:167], v[128:131]
	v_mfma_f32_16x16x32_bf16 v[116:119], v[148:151], v[188:191], v[116:119]
	v_mfma_f32_16x16x32_bf16 v[112:115], v[156:159], v[188:191], v[112:115]
	v_mfma_f32_16x16x32_bf16 v[100:103], v[148:151], v[196:199], v[100:103]
	v_mfma_f32_16x16x32_bf16 v[96:99], v[156:159], v[196:199], v[96:99]
	v_mfma_f32_16x16x32_bf16 v[72:75], v[148:151], v[204:207], v[72:75]
	v_mfma_f32_16x16x32_bf16 v[64:67], v[156:159], v[204:207], v[64:67]
	s_barrier
	s_add_i32 s50, s72, s43
	v_lshl_add_u64 v[170:171], v[170:171], 0, s[36:37]
	s_mov_b32 m0, s50
	ds_read_b128 v[160:163], v218 offset:49152
	ds_read_b128 v[164:167], v218 offset:50176
	ds_read_b128 v[184:187], v218 offset:51200
	ds_read_b128 v[188:191], v218 offset:52224
	ds_read_b128 v[192:195], v218 offset:53248
	ds_read_b128 v[196:199], v218 offset:54272
	ds_read_b128 v[200:203], v218 offset:55296
	ds_read_b128 v[204:207], v218 offset:56320
	global_load_lds_dwordx4 v[170:171], off
	s_add_i32 m0, s50, 0x2000
	s_add_u32 s50, s52, 0xb0080
	v_lshl_add_u64 v[170:171], v[172:173], 0, s[36:37]
	s_addc_u32 s51, s53, 0
	s_add_i32 s52, s73, s43
	global_load_lds_dwordx4 v[170:171], off
	v_lshl_add_u64 v[170:171], s[50:51], 0, v[168:169]
	s_mov_b32 m0, s52
	s_nop 0
	global_load_lds_dwordx4 v[170:171], off
	v_lshl_add_u64 v[170:171], s[50:51], 0, v[178:179]
	s_add_i32 m0, s52, 0x2000
	s_nop 0
	global_load_lds_dwordx4 v[170:171], off
	v_lshl_add_u64 v[170:171], v[208:209], 0, s[36:37]
	s_mov_b32 m0, s63
	s_nop 0
	global_load_lds_dwordx4 v[170:171], off
	v_lshl_add_u64 v[170:171], v[210:211], 0, s[36:37]
	s_mov_b32 m0, s64
	s_nop 0
	global_load_lds_dwordx4 v[170:171], off
	s_waitcnt vmcnt(8)
	s_waitcnt lgkmcnt(0)
	s_barrier
	s_waitcnt lgkmcnt(0)
	v_mfma_f32_16x16x32_bf16 v[60:63], v[68:71], v[160:163], v[60:63]
	v_mfma_f32_16x16x32_bf16 v[56:59], v[80:83], v[160:163], v[56:59]
	v_mfma_f32_16x16x32_bf16 v[44:47], v[68:71], v[184:187], v[44:47]
	v_mfma_f32_16x16x32_bf16 v[40:43], v[80:83], v[184:187], v[40:43]
	v_mfma_f32_16x16x32_bf16 v[28:31], v[68:71], v[192:195], v[28:31]
	v_mfma_f32_16x16x32_bf16 v[24:27], v[80:83], v[192:195], v[24:27]
	v_mfma_f32_16x16x32_bf16 v[12:15], v[68:71], v[200:203], v[12:15]
	v_mfma_f32_16x16x32_bf16 v[8:11], v[80:83], v[200:203], v[8:11]
	v_mfma_f32_16x16x32_bf16 v[60:63], v[76:79], v[164:167], v[60:63]
	v_mfma_f32_16x16x32_bf16 v[56:59], v[84:87], v[164:167], v[56:59]
	v_mfma_f32_16x16x32_bf16 v[44:47], v[76:79], v[188:191], v[44:47]
	v_mfma_f32_16x16x32_bf16 v[40:43], v[84:87], v[188:191], v[40:43]
	v_mfma_f32_16x16x32_bf16 v[28:31], v[76:79], v[196:199], v[28:31]
	v_mfma_f32_16x16x32_bf16 v[24:27], v[84:87], v[196:199], v[24:27]
	v_mfma_f32_16x16x32_bf16 v[12:15], v[76:79], v[204:207], v[12:15]
	v_mfma_f32_16x16x32_bf16 v[8:11], v[84:87], v[204:207], v[8:11]
	v_mfma_f32_16x16x32_bf16 v[52:55], v[144:147], v[160:163], v[52:55]
	v_mfma_f32_16x16x32_bf16 v[48:51], v[152:155], v[160:163], v[48:51]
	v_mfma_f32_16x16x32_bf16 v[36:39], v[144:147], v[184:187], v[36:39]
	v_mfma_f32_16x16x32_bf16 v[32:35], v[152:155], v[184:187], v[32:35]
	v_mfma_f32_16x16x32_bf16 v[20:23], v[144:147], v[192:195], v[20:23]
	v_mfma_f32_16x16x32_bf16 v[16:19], v[152:155], v[192:195], v[16:19]
	v_mfma_f32_16x16x32_bf16 v[4:7], v[144:147], v[200:203], v[4:7]
	v_mfma_f32_16x16x32_bf16 v[0:3], v[152:155], v[200:203], v[0:3]
	v_mfma_f32_16x16x32_bf16 v[52:55], v[148:151], v[164:167], v[52:55]
	v_mfma_f32_16x16x32_bf16 v[48:51], v[156:159], v[164:167], v[48:51]
	v_mfma_f32_16x16x32_bf16 v[36:39], v[148:151], v[188:191], v[36:39]
	v_mfma_f32_16x16x32_bf16 v[32:35], v[156:159], v[188:191], v[32:35]
	v_mfma_f32_16x16x32_bf16 v[20:23], v[148:151], v[196:199], v[20:23]
	v_mfma_f32_16x16x32_bf16 v[16:19], v[156:159], v[196:199], v[16:19]
	v_mfma_f32_16x16x32_bf16 v[4:7], v[148:151], v[204:207], v[4:7]
	v_mfma_f32_16x16x32_bf16 v[0:3], v[156:159], v[204:207], v[0:3]
	s_barrier
	s_add_i32 s71, s71, 2
	s_add_u32 s69, s69, 0x100
	s_addc_u32 s70, s70, 0
	s_cmp_gt_u32 s71, 41
	s_mov_b64 s[50:51], s[6:7]
	s_cbranch_scc0 .LBB0_843
	s_and_b64 vcc, exec, s[22:23]
	s_cbranch_vccz .LBB0_846
	s_barrier
